# baseline (speedup 1.0000x reference)
; #define LAS __attribute__((address_space(3)))
; DI float frcp(float x) { return __builtin_amdgcn_rcpf(x); }
; DI u32x2 pack4(const f32x4 a) { u32x2 w; w.x = cvt_pk_bf16(a[0], a[1]); w.y = cvt_pk_bf16(a[2], a[3]); return w; }
;     DI void operator()(const pg8::f32x4 (&acc)[2][2][4][2], const pg8::Unit& u, int wr, int wc, int fr, int fq) const {
;     ...
;         const LAS float* wl = (const LAS float*)(lds + CW_OFF) + wc * 32 + 8 * fq;
; #pragma unroll
;         for (int q = 0; q < 2; ++q) {
;             const f32x4 kg0 = *(const LAS f32x4*)(wl + 4 * q), kg1 = *(const LAS f32x4*)(wl + 128 + 4 * q), kg2 = *(const LAS f32x4*)(wl + 256 + 4 * q), bg = *(const LAS f32x4*)(wl + 384 + 4 * q);
;             const f32x4 kv0 = *(const LAS f32x4*)(wl + 512 + 4 * q), kv1 = *(const LAS f32x4*)(wl + 640 + 4 * q), kv2 = *(const LAS f32x4*)(wl + 768 + 4 * q), bv = *(const LAS f32x4*)(wl + 896 + 4 * q);
; #pragma unroll
;             for (int ai = 0; ai < 2; ++ai)
; #pragma unroll
;                 for (int m = 0; m < 4; ++m) {
;                     const f32x4 cg = acc[ai][0][m][q], cv = acc[ai][1][m][q];
;                     const f32x4 pg = m > 0 ? acc[ai][0][m > 0 ? m - 1 : 0][q] : (f32x4){0.f, 0.f, 0.f, 0.f}, pv = m > 0 ? acc[ai][1][m > 0 ? m - 1 : 0][q] : (f32x4){0.f, 0.f, 0.f, 0.f};
;                     f32x4 o;
; #pragma unroll
;                     for (int e = 0; e < 4; ++e) {
;                         const float g1 = row_shift<1>(cg[e], pg[e]), g2 = row_shift<2>(cg[e], pg[e]), v1 = row_shift<1>(cv[e], pv[e]), v2 = row_shift<2>(cv[e], pv[e]);
;                         const float a = bg[e] + kg0[e] * g2 + kg1[e] * g1 + kg2[e] * cg[e], b = bv[e] + kv0[e] * v2 + kv1[e] * v1 + kv2[e] * cv[e];
;                         o[e] = a * frcp(1.f + __expf(-a)) * b;
;                     }
;                     const int r = u.pm * 256 + ai * 128 + wr * 64 + m * 16 + fr;
;                     if (m > 0 || fr >= 2) *(u32x2*)(ACT + (size_t)r * DFF + j0 + 4 * q) = pack4(o);
;                     __builtin_amdgcn_sched_barrier(0);
;                 }
.LBB0_832:
	s_or_b64 exec, exec, s[40:41]
	v_mov_b32_dpp v143, v127 row_ror:2 row_mask:0xf bank_mask:0xf
	v_mov_b32_dpp v142, v119 row_ror:2 row_mask:0xf bank_mask:0xf
	v_mov_b32_dpp v141, v127 row_ror:1 row_mask:0xf bank_mask:0xf
	v_mov_b32_dpp v143, v111 row_shr:2 row_mask:0xf bank_mask:0xf
	v_mov_b32_dpp v140, v119 row_ror:1 row_mask:0xf bank_mask:0xf
	v_mov_b32_dpp v142, v103 row_shr:2 row_mask:0xf bank_mask:0xf
	v_mov_b32_dpp v141, v111 row_shr:1 row_mask:0xf bank_mask:0xf
	v_mov_b32_dpp v140, v103 row_shr:1 row_mask:0xf bank_mask:0xf
	v_pk_fma_f32 v[142:143], v[212:213], v[142:143], v[214:215]
	v_pk_fma_f32 v[140:141], v[210:211], v[140:141], v[142:143]
	v_fmac_f32_e32 v140, v103, v208
	v_fmac_f32_e32 v141, v111, v209
	v_mul_f32_e32 v138, 0xbfb8aa3b, v141
	v_exp_f32_e32 v142, v138
	v_mov_b32_dpp v139, v126 row_ror:2 row_mask:0xf bank_mask:0xf
	v_mov_b32_dpp v138, v118 row_ror:2 row_mask:0xf bank_mask:0xf
	v_mov_b32_dpp v137, v126 row_ror:1 row_mask:0xf bank_mask:0xf
	v_mov_b32_dpp v139, v110 row_shr:2 row_mask:0xf bank_mask:0xf
	v_mov_b32_dpp v136, v118 row_ror:1 row_mask:0xf bank_mask:0xf
	v_mov_b32_dpp v138, v102 row_shr:2 row_mask:0xf bank_mask:0xf
	v_mov_b32_dpp v137, v110 row_shr:1 row_mask:0xf bank_mask:0xf
	v_mov_b32_dpp v136, v102 row_shr:1 row_mask:0xf bank_mask:0xf
	v_add_f32_e32 v142, 1.0, v142
	v_pk_fma_f32 v[138:139], v[218:219], v[138:139], v[216:217]
	v_rcp_f32_e32 v144, v142
	v_pk_fma_f32 v[136:137], v[220:221], v[136:137], v[138:139]
	v_fmac_f32_e32 v136, v102, v222
	v_fmac_f32_e32 v137, v110, v223
	v_mul_f32_e32 v138, 0xbfb8aa3b, v137
	v_exp_f32_e32 v138, v138
	v_mov_b32_dpp v135, v125 row_ror:2 row_mask:0xf bank_mask:0xf
	v_mov_b32_dpp v134, v117 row_ror:2 row_mask:0xf bank_mask:0xf
	v_mov_b32_dpp v133, v125 row_ror:1 row_mask:0xf bank_mask:0xf
	v_mov_b32_dpp v135, v109 row_shr:2 row_mask:0xf bank_mask:0xf
	v_mov_b32_dpp v132, v117 row_ror:1 row_mask:0xf bank_mask:0xf
	v_mov_b32_dpp v134, v101 row_shr:2 row_mask:0xf bank_mask:0xf
	v_mov_b32_dpp v133, v109 row_shr:1 row_mask:0xf bank_mask:0xf
	v_mov_b32_dpp v132, v101 row_shr:1 row_mask:0xf bank_mask:0xf
	v_mul_f32_e32 v139, v141, v144
	v_add_f32_e32 v138, 1.0, v138
	v_pk_fma_f32 v[134:135], v[196:197], v[134:135], v[198:199]
	v_mov_b32_dpp v131, v124 row_ror:2 row_mask:0xf bank_mask:0xf
	v_mov_b32_dpp v130, v116 row_ror:2 row_mask:0xf bank_mask:0xf
	v_mul_f32_e32 v140, v140, v139
	v_rcp_f32_e32 v141, v138
	v_pk_fma_f32 v[132:133], v[194:195], v[132:133], v[134:135]
	v_mov_b32_dpp v129, v124 row_ror:1 row_mask:0xf bank_mask:0xf
	v_mov_b32_dpp v131, v108 row_shr:2 row_mask:0xf bank_mask:0xf
	v_mov_b32_dpp v128, v116 row_ror:1 row_mask:0xf bank_mask:0xf
	v_mov_b32_dpp v130, v100 row_shr:2 row_mask:0xf bank_mask:0xf
	v_fmac_f32_e32 v132, v101, v192
	v_fmac_f32_e32 v133, v109, v193
	v_mov_b32_dpp v129, v108 row_shr:1 row_mask:0xf bank_mask:0xf
	v_mov_b32_dpp v128, v100 row_shr:1 row_mask:0xf bank_mask:0xf
	v_mul_f32_e32 v134, 0xbfb8aa3b, v133
	v_pk_fma_f32 v[130:131], v[202:203], v[130:131], v[200:201]
	v_exp_f32_e32 v138, v134
	v_pk_fma_f32 v[128:129], v[204:205], v[128:129], v[130:131]
	v_mul_f32_e32 v131, v137, v141
	v_fmac_f32_e32 v128, v100, v206
	v_fmac_f32_e32 v129, v108, v207
	v_add_f32_e32 v134, 1.0, v138
	v_mul_f32_e32 v130, 0xbfb8aa3b, v129
	v_exp_f32_e32 v130, v130
	v_rcp_f32_e32 v134, v134
	v_mul_f32_e32 v131, v136, v131
	v_add_f32_e32 v130, 1.0, v130
	v_rcp_f32_e32 v130, v130
	v_mul_f32_e32 v133, v133, v134
	v_mul_f32_e32 v132, v132, v133
	v_mul_f32_e32 v129, v129, v130
	v_mul_f32_e32 v128, v128, v129
	v_add_u32_e32 v129, 16, v164
	v_cvt_pk_bf16_f32 v132, v128, v132
	v_cvt_pk_bf16_f32 v133, v131, v140
	v_mov_b64_e32 v[130:131], s[66:67]
	v_mad_i64_i32 v[134:135], s[14:15], v129, s97, v[130:131]
	v_lshlrev_b64 v[128:129], 1, v[178:179]
	v_lshl_add_u64 v[182:183], v[134:135], 0, v[128:129]
	global_store_dwordx2 v[182:183], v[132:133], off
	v_mov_b32_dpp v147, v111 row_ror:2 row_mask:0xf bank_mask:0xf
	v_mov_b32_dpp v146, v103 row_ror:2 row_mask:0xf bank_mask:0xf
	v_mov_b32_dpp v145, v111 row_ror:1 row_mask:0xf bank_mask:0xf
	v_mov_b32_dpp v147, v95 row_shr:2 row_mask:0xf bank_mask:0xf
	v_mov_b32_dpp v144, v103 row_ror:1 row_mask:0xf bank_mask:0xf
	v_mov_b32_dpp v146, v87 row_shr:2 row_mask:0xf bank_mask:0xf
	v_mov_b32_dpp v145, v95 row_shr:1 row_mask:0xf bank_mask:0xf
	v_mov_b32_dpp v144, v87 row_shr:1 row_mask:0xf bank_mask:0xf
	v_pk_fma_f32 v[146:147], v[212:213], v[146:147], v[214:215]
	v_pk_fma_f32 v[144:145], v[210:211], v[144:145], v[146:147]
	v_fmac_f32_e32 v144, v87, v208
	v_fmac_f32_e32 v145, v95, v209
	v_mul_f32_e32 v142, 0xbfb8aa3b, v145
	v_exp_f32_e32 v146, v142
	v_mov_b32_dpp v143, v110 row_ror:2 row_mask:0xf bank_mask:0xf
	v_mov_b32_dpp v142, v102 row_ror:2 row_mask:0xf bank_mask:0xf
	v_mov_b32_dpp v141, v110 row_ror:1 row_mask:0xf bank_mask:0xf
	v_mov_b32_dpp v143, v94 row_shr:2 row_mask:0xf bank_mask:0xf
	v_mov_b32_dpp v140, v102 row_ror:1 row_mask:0xf bank_mask:0xf
	v_mov_b32_dpp v142, v86 row_shr:2 row_mask:0xf bank_mask:0xf
	v_mov_b32_dpp v141, v94 row_shr:1 row_mask:0xf bank_mask:0xf
	v_mov_b32_dpp v140, v86 row_shr:1 row_mask:0xf bank_mask:0xf
	v_add_f32_e32 v146, 1.0, v146
	v_pk_fma_f32 v[142:143], v[218:219], v[142:143], v[216:217]
	v_rcp_f32_e32 v148, v146
	v_pk_fma_f32 v[140:141], v[220:221], v[140:141], v[142:143]
	v_fmac_f32_e32 v140, v86, v222
	v_fmac_f32_e32 v141, v94, v223
	v_mul_f32_e32 v142, 0xbfb8aa3b, v141
	v_exp_f32_e32 v142, v142
	v_mov_b32_dpp v139, v109 row_ror:2 row_mask:0xf bank_mask:0xf
	v_mov_b32_dpp v138, v101 row_ror:2 row_mask:0xf bank_mask:0xf
	v_mov_b32_dpp v137, v109 row_ror:1 row_mask:0xf bank_mask:0xf
; #define LAS __attribute__((address_space(3)))
; DI float frcp(float x) { return __builtin_amdgcn_rcpf(x); }
; DI u32x2 pack4(const f32x4 a) { u32x2 w; w.x = cvt_pk_bf16(a[0], a[1]); w.y = cvt_pk_bf16(a[2], a[3]); return w; }
;     DI void operator()(const pg8::f32x4 (&acc)[2][2][4][2], const pg8::Unit& u, int wr, int wc, int fr, int fq) const {
;     ...
;         const LAS float* wl = (const LAS float*)(lds + CW_OFF) + wc * 32 + 8 * fq;
; #pragma unroll
;         for (int q = 0; q < 2; ++q) {
;             const f32x4 kg0 = *(const LAS f32x4*)(wl + 4 * q), kg1 = *(const LAS f32x4*)(wl + 128 + 4 * q), kg2 = *(const LAS f32x4*)(wl + 256 + 4 * q), bg = *(const LAS f32x4*)(wl + 384 + 4 * q);
;             const f32x4 kv0 = *(const LAS f32x4*)(wl + 512 + 4 * q), kv1 = *(const LAS f32x4*)(wl + 640 + 4 * q), kv2 = *(const LAS f32x4*)(wl + 768 + 4 * q), bv = *(const LAS f32x4*)(wl + 896 + 4 * q);
; #pragma unroll
;             for (int ai = 0; ai < 2; ++ai)
; #pragma unroll
;                 for (int m = 0; m < 4; ++m) {
;                     const f32x4 cg = acc[ai][0][m][q], cv = acc[ai][1][m][q];
;                     const f32x4 pg = m > 0 ? acc[ai][0][m > 0 ? m - 1 : 0][q] : (f32x4){0.f, 0.f, 0.f, 0.f}, pv = m > 0 ? acc[ai][1][m > 0 ? m - 1 : 0][q] : (f32x4){0.f, 0.f, 0.f, 0.f};
;                     f32x4 o;
; #pragma unroll
;                     for (int e = 0; e < 4; ++e) {
;                         const float g1 = row_shift<1>(cg[e], pg[e]), g2 = row_shift<2>(cg[e], pg[e]), v1 = row_shift<1>(cv[e], pv[e]), v2 = row_shift<2>(cv[e], pv[e]);
;                         const float a = bg[e] + kg0[e] * g2 + kg1[e] * g1 + kg2[e] * cg[e], b = bv[e] + kv0[e] * v2 + kv1[e] * v1 + kv2[e] * cv[e];
;                         o[e] = a * frcp(1.f + __expf(-a)) * b;
;                     }
;                     const int r = u.pm * 256 + ai * 128 + wr * 64 + m * 16 + fr;
;                     if (m > 0 || fr >= 2) *(u32x2*)(ACT + (size_t)r * DFF + j0 + 4 * q) = pack4(o);
;                     __builtin_amdgcn_sched_barrier(0);
;                 }
	v_mov_b32_dpp v139, v93 row_shr:2 row_mask:0xf bank_mask:0xf
	v_mov_b32_dpp v136, v101 row_ror:1 row_mask:0xf bank_mask:0xf
	v_mov_b32_dpp v138, v85 row_shr:2 row_mask:0xf bank_mask:0xf
	v_mov_b32_dpp v137, v93 row_shr:1 row_mask:0xf bank_mask:0xf
	v_mov_b32_dpp v136, v85 row_shr:1 row_mask:0xf bank_mask:0xf
	v_mul_f32_e32 v143, v145, v148
	v_add_f32_e32 v142, 1.0, v142
	v_pk_fma_f32 v[138:139], v[196:197], v[138:139], v[198:199]
	v_mov_b32_dpp v135, v108 row_ror:2 row_mask:0xf bank_mask:0xf
	v_mov_b32_dpp v134, v100 row_ror:2 row_mask:0xf bank_mask:0xf
	v_mul_f32_e32 v144, v144, v143
	v_rcp_f32_e32 v145, v142
	v_pk_fma_f32 v[136:137], v[194:195], v[136:137], v[138:139]
	v_mov_b32_dpp v133, v108 row_ror:1 row_mask:0xf bank_mask:0xf
	v_mov_b32_dpp v135, v92 row_shr:2 row_mask:0xf bank_mask:0xf
	v_mov_b32_dpp v132, v100 row_ror:1 row_mask:0xf bank_mask:0xf
	v_mov_b32_dpp v134, v84 row_shr:2 row_mask:0xf bank_mask:0xf
	v_fmac_f32_e32 v136, v85, v192
	v_fmac_f32_e32 v137, v93, v193
	v_mov_b32_dpp v133, v92 row_shr:1 row_mask:0xf bank_mask:0xf
	v_mov_b32_dpp v132, v84 row_shr:1 row_mask:0xf bank_mask:0xf
	v_mul_f32_e32 v138, 0xbfb8aa3b, v137
	v_pk_fma_f32 v[134:135], v[202:203], v[134:135], v[200:201]
	v_exp_f32_e32 v142, v138
	v_pk_fma_f32 v[132:133], v[204:205], v[132:133], v[134:135]
	v_mul_f32_e32 v135, v141, v145
	v_fmac_f32_e32 v132, v84, v206
	v_fmac_f32_e32 v133, v92, v207
	v_add_f32_e32 v138, 1.0, v142
	v_mul_f32_e32 v134, 0xbfb8aa3b, v133
	v_exp_f32_e32 v134, v134
	v_rcp_f32_e32 v138, v138
	v_mul_f32_e32 v135, v140, v135
	v_add_f32_e32 v134, 1.0, v134
	v_rcp_f32_e32 v134, v134
	v_mul_f32_e32 v137, v137, v138
	v_mul_f32_e32 v136, v136, v137
	v_mul_f32_e32 v133, v133, v134
	v_mul_f32_e32 v132, v132, v133
	v_add_u32_e32 v134, 32, v164
	v_cvt_pk_bf16_f32 v132, v132, v136
	v_cvt_pk_bf16_f32 v133, v135, v144
	v_mad_i64_i32 v[134:135], s[14:15], v134, s97, v[130:131]
	v_lshl_add_u64 v[184:185], v[134:135], 0, v[128:129]
	global_store_dwordx2 v[184:185], v[132:133], off
	v_mov_b32_dpp v147, v95 row_ror:2 row_mask:0xf bank_mask:0xf
	v_mov_b32_dpp v146, v87 row_ror:2 row_mask:0xf bank_mask:0xf
	v_mov_b32_dpp v145, v95 row_ror:1 row_mask:0xf bank_mask:0xf
	v_mov_b32_dpp v147, v79 row_shr:2 row_mask:0xf bank_mask:0xf
	v_mov_b32_dpp v144, v87 row_ror:1 row_mask:0xf bank_mask:0xf
	v_mov_b32_dpp v146, v71 row_shr:2 row_mask:0xf bank_mask:0xf
	v_mov_b32_dpp v145, v79 row_shr:1 row_mask:0xf bank_mask:0xf
	v_mov_b32_dpp v144, v71 row_shr:1 row_mask:0xf bank_mask:0xf
	v_pk_fma_f32 v[146:147], v[212:213], v[146:147], v[214:215]
	v_pk_fma_f32 v[144:145], v[210:211], v[144:145], v[146:147]
	v_fmac_f32_e32 v144, v71, v208
	v_fmac_f32_e32 v145, v79, v209
	v_mul_f32_e32 v142, 0xbfb8aa3b, v145
	v_exp_f32_e32 v146, v142
	v_mov_b32_dpp v143, v94 row_ror:2 row_mask:0xf bank_mask:0xf
	v_mov_b32_dpp v142, v86 row_ror:2 row_mask:0xf bank_mask:0xf
	v_mov_b32_dpp v141, v94 row_ror:1 row_mask:0xf bank_mask:0xf
	v_mov_b32_dpp v143, v78 row_shr:2 row_mask:0xf bank_mask:0xf
	v_mov_b32_dpp v140, v86 row_ror:1 row_mask:0xf bank_mask:0xf
	v_mov_b32_dpp v142, v70 row_shr:2 row_mask:0xf bank_mask:0xf
	v_mov_b32_dpp v141, v78 row_shr:1 row_mask:0xf bank_mask:0xf
	v_mov_b32_dpp v140, v70 row_shr:1 row_mask:0xf bank_mask:0xf
	v_add_f32_e32 v146, 1.0, v146
	v_pk_fma_f32 v[142:143], v[218:219], v[142:143], v[216:217]
	v_rcp_f32_e32 v148, v146
	v_pk_fma_f32 v[140:141], v[220:221], v[140:141], v[142:143]
	v_fmac_f32_e32 v140, v70, v222
	v_fmac_f32_e32 v141, v78, v223
	v_mul_f32_e32 v142, 0xbfb8aa3b, v141
	v_exp_f32_e32 v142, v142
	v_mov_b32_dpp v139, v93 row_ror:2 row_mask:0xf bank_mask:0xf
	v_mov_b32_dpp v138, v85 row_ror:2 row_mask:0xf bank_mask:0xf
	v_mov_b32_dpp v137, v93 row_ror:1 row_mask:0xf bank_mask:0xf
	v_mov_b32_dpp v139, v77 row_shr:2 row_mask:0xf bank_mask:0xf
	v_mov_b32_dpp v136, v85 row_ror:1 row_mask:0xf bank_mask:0xf
	v_mov_b32_dpp v138, v69 row_shr:2 row_mask:0xf bank_mask:0xf
	v_mov_b32_dpp v137, v77 row_shr:1 row_mask:0xf bank_mask:0xf
	v_mov_b32_dpp v136, v69 row_shr:1 row_mask:0xf bank_mask:0xf
	v_mul_f32_e32 v143, v145, v148
	v_add_f32_e32 v142, 1.0, v142
	v_pk_fma_f32 v[138:139], v[196:197], v[138:139], v[198:199]
	v_mov_b32_dpp v135, v92 row_ror:2 row_mask:0xf bank_mask:0xf
	v_mov_b32_dpp v134, v84 row_ror:2 row_mask:0xf bank_mask:0xf
	v_mul_f32_e32 v144, v144, v143
	v_rcp_f32_e32 v145, v142
	v_pk_fma_f32 v[136:137], v[194:195], v[136:137], v[138:139]
	v_mov_b32_dpp v133, v92 row_ror:1 row_mask:0xf bank_mask:0xf
	v_mov_b32_dpp v135, v76 row_shr:2 row_mask:0xf bank_mask:0xf
	v_mov_b32_dpp v132, v84 row_ror:1 row_mask:0xf bank_mask:0xf
	v_mov_b32_dpp v134, v68 row_shr:2 row_mask:0xf bank_mask:0xf
	v_fmac_f32_e32 v136, v69, v192
	v_fmac_f32_e32 v137, v77, v193
	v_mov_b32_dpp v133, v76 row_shr:1 row_mask:0xf bank_mask:0xf
	v_mov_b32_dpp v132, v68 row_shr:1 row_mask:0xf bank_mask:0xf
	v_mul_f32_e32 v138, 0xbfb8aa3b, v137
	v_pk_fma_f32 v[134:135], v[202:203], v[134:135], v[200:201]
	v_exp_f32_e32 v142, v138
	v_pk_fma_f32 v[132:133], v[204:205], v[132:133], v[134:135]
	v_mul_f32_e32 v135, v141, v145
	v_fmac_f32_e32 v132, v68, v206
	v_fmac_f32_e32 v133, v76, v207
	v_add_f32_e32 v138, 1.0, v142
	v_mul_f32_e32 v134, 0xbfb8aa3b, v133
	v_exp_f32_e32 v134, v134
	v_rcp_f32_e32 v138, v138
	v_mad_i64_i32 v[130:131], s[14:15], v230, s97, v[130:131]
	v_add_f32_e32 v134, 1.0, v134
	v_rcp_f32_e32 v134, v134
	v_mul_f32_e32 v137, v137, v138
	v_mul_f32_e32 v135, v140, v135
	v_mul_f32_e32 v136, v136, v137
	v_mul_f32_e32 v133, v133, v134
	v_mul_f32_e32 v132, v132, v133
	v_lshl_add_u64 v[186:187], v[130:131], 0, v[128:129]
	v_cvt_pk_bf16_f32 v132, v132, v136
	v_cvt_pk_bf16_f32 v133, v135, v144
; DI float frcp(float x) { return __builtin_amdgcn_rcpf(x); }
; DI u32x2 pack4(const f32x4 a) { u32x2 w; w.x = cvt_pk_bf16(a[0], a[1]); w.y = cvt_pk_bf16(a[2], a[3]); return w; }
;     DI void operator()(const pg8::f32x4 (&acc)[2][2][4][2], const pg8::Unit& u, int wr, int wc, int fr, int fq) const {
;     ...
;                     const f32x4 pg = m > 0 ? acc[ai][0][m > 0 ? m - 1 : 0][q] : (f32x4){0.f, 0.f, 0.f, 0.f}, pv = m > 0 ? acc[ai][1][m > 0 ? m - 1 : 0][q] : (f32x4){0.f, 0.f, 0.f, 0.f};
;                     f32x4 o;
; #pragma unroll
;                     for (int e = 0; e < 4; ++e) {
;                         const float g1 = row_shift<1>(cg[e], pg[e]), g2 = row_shift<2>(cg[e], pg[e]), v1 = row_shift<1>(cv[e], pv[e]), v2 = row_shift<2>(cv[e], pv[e]);
;                         const float a = bg[e] + kg0[e] * g2 + kg1[e] * g1 + kg2[e] * cg[e], b = bv[e] + kv0[e] * v2 + kv1[e] * v1 + kv2[e] * cv[e];
;                         o[e] = a * frcp(1.f + __expf(-a)) * b;
;                     }
;                     const int r = u.pm * 256 + ai * 128 + wr * 64 + m * 16 + fr;
;                     if (m > 0 || fr >= 2) *(u32x2*)(ACT + (size_t)r * DFF + j0 + 4 * q) = pack4(o);
;                     __builtin_amdgcn_sched_barrier(0);
;                 }
	global_store_dwordx2 v[186:187], v[132:133], off
	v_mov_b32_e32 v138, v161
	v_mov_b32_e32 v144, v161
	s_nop 0
	v_mov_b32_dpp v138, v138 row_ror:1 row_mask:0xf bank_mask:0xf
	v_mov_b32_dpp v144, v144 row_ror:2 row_mask:0xf bank_mask:0xf
	v_mov_b32_e32 v131, v138
	v_mov_b32_e32 v133, v144
	v_mov_b32_e32 v130, v138
	v_mov_b32_e32 v132, v144
	v_mov_b32_e32 v135, v138
	v_mov_b32_e32 v137, v144
	v_mov_b32_e32 v134, v138
	v_mov_b32_e32 v136, v144
	v_mov_b32_e32 v141, v138
	v_mov_b32_e32 v143, v144
	v_mov_b32_e32 v140, v138
	v_mov_b32_e32 v142, v144
	v_mov_b32_e32 v139, v138
	v_mov_b32_e32 v145, v144
	v_mov_b32_dpp v131, v60 row_shr:1 row_mask:0xf bank_mask:0xf
	v_mov_b32_dpp v133, v60 row_shr:2 row_mask:0xf bank_mask:0xf
	v_mov_b32_dpp v130, v52 row_shr:1 row_mask:0xf bank_mask:0xf
	v_mov_b32_dpp v132, v52 row_shr:2 row_mask:0xf bank_mask:0xf
	v_mov_b32_dpp v135, v61 row_shr:1 row_mask:0xf bank_mask:0xf
	v_mov_b32_dpp v137, v61 row_shr:2 row_mask:0xf bank_mask:0xf
	v_mov_b32_dpp v134, v53 row_shr:1 row_mask:0xf bank_mask:0xf
	v_mov_b32_dpp v136, v53 row_shr:2 row_mask:0xf bank_mask:0xf
	v_mov_b32_dpp v141, v62 row_shr:1 row_mask:0xf bank_mask:0xf
	v_mov_b32_dpp v143, v62 row_shr:2 row_mask:0xf bank_mask:0xf
	v_mov_b32_dpp v140, v54 row_shr:1 row_mask:0xf bank_mask:0xf
	v_mov_b32_dpp v142, v54 row_shr:2 row_mask:0xf bank_mask:0xf
	v_mov_b32_dpp v139, v63 row_shr:1 row_mask:0xf bank_mask:0xf
	v_mov_b32_dpp v145, v63 row_shr:2 row_mask:0xf bank_mask:0xf
	v_mov_b32_dpp v138, v55 row_shr:1 row_mask:0xf bank_mask:0xf
	v_mov_b32_dpp v144, v55 row_shr:2 row_mask:0xf bank_mask:0xf
	s_and_saveexec_b64 s[40:41], vcc
	s_cbranch_execz .LBB0_834
	v_pk_fma_f32 v[144:145], v[212:213], v[144:145], v[214:215]
	v_pk_fma_f32 v[138:139], v[210:211], v[138:139], v[144:145]
	v_pk_fma_f32 v[142:143], v[218:219], v[142:143], v[216:217]
	v_fmac_f32_e32 v138, v55, v208
	v_fmac_f32_e32 v139, v63, v209
	v_pk_fma_f32 v[140:141], v[220:221], v[140:141], v[142:143]
	v_mul_f32_e32 v144, 0xbfb8aa3b, v139
	v_exp_f32_e32 v145, v144
	v_pk_fma_f32 v[136:137], v[196:197], v[136:137], v[198:199]
	v_pk_fma_f32 v[132:133], v[202:203], v[132:133], v[200:201]
	v_add_f32_e32 v145, 1.0, v145
	v_rcp_f32_e32 v146, v145
	v_fmac_f32_e32 v140, v54, v222
	v_fmac_f32_e32 v141, v62, v223
	v_pk_fma_f32 v[134:135], v[194:195], v[134:135], v[136:137]
	v_mul_f32_e32 v142, 0xbfb8aa3b, v141
	v_exp_f32_e32 v142, v142
	v_mul_f32_e32 v139, v139, v146
	v_mul_f32_e32 v143, v138, v139
	v_add_f32_e32 v138, 1.0, v142
	v_rcp_f32_e32 v142, v138
	v_fmac_f32_e32 v134, v53, v192
	v_fmac_f32_e32 v135, v61, v193
	v_mul_f32_e32 v136, 0xbfb8aa3b, v135
	v_exp_f32_e32 v138, v136
	v_pk_fma_f32 v[130:131], v[204:205], v[130:131], v[132:133]
	v_mul_f32_e32 v133, v141, v142
	v_fmac_f32_e32 v130, v52, v206
	v_fmac_f32_e32 v131, v60, v207
	v_add_f32_e32 v136, 1.0, v138
	v_mul_f32_e32 v132, 0xbfb8aa3b, v131
	v_exp_f32_e32 v132, v132
	v_rcp_f32_e32 v136, v136
	v_mul_f32_e32 v133, v140, v133
	v_add_f32_e32 v132, 1.0, v132
	v_rcp_f32_e32 v132, v132
	v_mul_f32_e32 v135, v135, v136
	v_mul_f32_e32 v134, v134, v135
	v_mul_f32_e32 v131, v131, v132
	v_mul_f32_e32 v130, v130, v131
	v_cvt_pk_bf16_f32 v130, v130, v134
	v_cvt_pk_bf16_f32 v131, v133, v143
	v_mov_b64_e32 v[132:133], s[66:67]
	v_mad_i64_i32 v[132:133], s[14:15], v163, s97, v[132:133]
	v_lshl_add_u64 v[132:133], v[178:179], 1, v[132:133]
	global_store_dwordx2 v[132:133], v[130:131], off
.LBB0_834:
	s_or_b64 exec, exec, s[40:41]
	v_mov_b32_dpp v145, v63 row_ror:2 row_mask:0xf bank_mask:0xf
	v_mov_b32_dpp v144, v55 row_ror:2 row_mask:0xf bank_mask:0xf
	v_mov_b32_dpp v143, v63 row_ror:1 row_mask:0xf bank_mask:0xf
	v_mov_b32_dpp v145, v47 row_shr:2 row_mask:0xf bank_mask:0xf
	v_mov_b32_dpp v142, v55 row_ror:1 row_mask:0xf bank_mask:0xf
	v_mov_b32_dpp v144, v39 row_shr:2 row_mask:0xf bank_mask:0xf
	v_mov_b32_dpp v143, v47 row_shr:1 row_mask:0xf bank_mask:0xf
	v_mov_b32_dpp v142, v39 row_shr:1 row_mask:0xf bank_mask:0xf
	v_pk_fma_f32 v[144:145], v[212:213], v[144:145], v[214:215]
	v_pk_fma_f32 v[142:143], v[210:211], v[142:143], v[144:145]
	v_fmac_f32_e32 v142, v39, v208
	v_fmac_f32_e32 v143, v47, v209
	v_mul_f32_e32 v140, 0xbfb8aa3b, v143
	v_exp_f32_e32 v144, v140
	v_mov_b32_dpp v141, v62 row_ror:2 row_mask:0xf bank_mask:0xf
	v_mov_b32_dpp v140, v54 row_ror:2 row_mask:0xf bank_mask:0xf
	v_mov_b32_dpp v139, v62 row_ror:1 row_mask:0xf bank_mask:0xf
	v_mov_b32_dpp v141, v46 row_shr:2 row_mask:0xf bank_mask:0xf
	v_mov_b32_dpp v138, v54 row_ror:1 row_mask:0xf bank_mask:0xf
	v_mov_b32_dpp v140, v38 row_shr:2 row_mask:0xf bank_mask:0xf
	v_mov_b32_dpp v139, v46 row_shr:1 row_mask:0xf bank_mask:0xf
	v_mov_b32_dpp v138, v38 row_shr:1 row_mask:0xf bank_mask:0xf
	v_add_f32_e32 v144, 1.0, v144
	v_pk_fma_f32 v[140:141], v[218:219], v[140:141], v[216:217]
	v_rcp_f32_e32 v146, v144
	v_pk_fma_f32 v[138:139], v[220:221], v[138:139], v[140:141]
	v_fmac_f32_e32 v138, v38, v222
	v_fmac_f32_e32 v139, v46, v223
	v_mul_f32_e32 v140, 0xbfb8aa3b, v139
	v_exp_f32_e32 v140, v140
	v_mov_b32_dpp v137, v61 row_ror:2 row_mask:0xf bank_mask:0xf
	v_mov_b32_dpp v136, v53 row_ror:2 row_mask:0xf bank_mask:0xf
	v_mov_b32_dpp v135, v61 row_ror:1 row_mask:0xf bank_mask:0xf
	v_mov_b32_dpp v137, v45 row_shr:2 row_mask:0xf bank_mask:0xf
	v_mov_b32_dpp v134, v53 row_ror:1 row_mask:0xf bank_mask:0xf
	v_mov_b32_dpp v136, v37 row_shr:2 row_mask:0xf bank_mask:0xf
	v_mov_b32_dpp v135, v45 row_shr:1 row_mask:0xf bank_mask:0xf
	v_mov_b32_dpp v134, v37 row_shr:1 row_mask:0xf bank_mask:0xf
	v_mul_f32_e32 v141, v143, v146
	v_add_f32_e32 v140, 1.0, v140
	v_pk_fma_f32 v[136:137], v[196:197], v[136:137], v[198:199]
; #define LAS __attribute__((address_space(3)))
; DI float frcp(float x) { return __builtin_amdgcn_rcpf(x); }
; DI u32x2 pack4(const f32x4 a) { u32x2 w; w.x = cvt_pk_bf16(a[0], a[1]); w.y = cvt_pk_bf16(a[2], a[3]); return w; }
;     DI void operator()(const pg8::f32x4 (&acc)[2][2][4][2], const pg8::Unit& u, int wr, int wc, int fr, int fq) const {
;     ...
;         const LAS float* wl = (const LAS float*)(lds + CW_OFF) + wc * 32 + 8 * fq;
; #pragma unroll
;         for (int q = 0; q < 2; ++q) {
;             const f32x4 kg0 = *(const LAS f32x4*)(wl + 4 * q), kg1 = *(const LAS f32x4*)(wl + 128 + 4 * q), kg2 = *(const LAS f32x4*)(wl + 256 + 4 * q), bg = *(const LAS f32x4*)(wl + 384 + 4 * q);
;             const f32x4 kv0 = *(const LAS f32x4*)(wl + 512 + 4 * q), kv1 = *(const LAS f32x4*)(wl + 640 + 4 * q), kv2 = *(const LAS f32x4*)(wl + 768 + 4 * q), bv = *(const LAS f32x4*)(wl + 896 + 4 * q);
; #pragma unroll
;             for (int ai = 0; ai < 2; ++ai)
; #pragma unroll
;                 for (int m = 0; m < 4; ++m) {
;                     const f32x4 cg = acc[ai][0][m][q], cv = acc[ai][1][m][q];
;                     const f32x4 pg = m > 0 ? acc[ai][0][m > 0 ? m - 1 : 0][q] : (f32x4){0.f, 0.f, 0.f, 0.f}, pv = m > 0 ? acc[ai][1][m > 0 ? m - 1 : 0][q] : (f32x4){0.f, 0.f, 0.f, 0.f};
;                     f32x4 o;
; #pragma unroll
;                     for (int e = 0; e < 4; ++e) {
;                         const float g1 = row_shift<1>(cg[e], pg[e]), g2 = row_shift<2>(cg[e], pg[e]), v1 = row_shift<1>(cv[e], pv[e]), v2 = row_shift<2>(cv[e], pv[e]);
;                         const float a = bg[e] + kg0[e] * g2 + kg1[e] * g1 + kg2[e] * cg[e], b = bv[e] + kv0[e] * v2 + kv1[e] * v1 + kv2[e] * cv[e];
;                         o[e] = a * frcp(1.f + __expf(-a)) * b;
;                     }
;                     const int r = u.pm * 256 + ai * 128 + wr * 64 + m * 16 + fr;
;                     if (m > 0 || fr >= 2) *(u32x2*)(ACT + (size_t)r * DFF + j0 + 4 * q) = pack4(o);
;                     __builtin_amdgcn_sched_barrier(0);
;                 }
	v_mov_b32_dpp v133, v60 row_ror:2 row_mask:0xf bank_mask:0xf
	v_mov_b32_dpp v132, v52 row_ror:2 row_mask:0xf bank_mask:0xf
	v_mul_f32_e32 v142, v142, v141
	v_rcp_f32_e32 v143, v140
	v_pk_fma_f32 v[134:135], v[194:195], v[134:135], v[136:137]
	v_mov_b32_dpp v131, v60 row_ror:1 row_mask:0xf bank_mask:0xf
	v_mov_b32_dpp v133, v44 row_shr:2 row_mask:0xf bank_mask:0xf
	v_mov_b32_dpp v130, v52 row_ror:1 row_mask:0xf bank_mask:0xf
	v_mov_b32_dpp v132, v36 row_shr:2 row_mask:0xf bank_mask:0xf
	v_fmac_f32_e32 v134, v37, v192
	v_fmac_f32_e32 v135, v45, v193
	v_mov_b32_dpp v131, v44 row_shr:1 row_mask:0xf bank_mask:0xf
	v_mov_b32_dpp v130, v36 row_shr:1 row_mask:0xf bank_mask:0xf
	v_mul_f32_e32 v136, 0xbfb8aa3b, v135
	v_pk_fma_f32 v[132:133], v[202:203], v[132:133], v[200:201]
	v_exp_f32_e32 v140, v136
	v_pk_fma_f32 v[130:131], v[204:205], v[130:131], v[132:133]
	v_mul_f32_e32 v133, v139, v143
	v_fmac_f32_e32 v130, v36, v206
	v_fmac_f32_e32 v131, v44, v207
	v_add_f32_e32 v136, 1.0, v140
	v_mul_f32_e32 v132, 0xbfb8aa3b, v131
	v_exp_f32_e32 v132, v132
	v_rcp_f32_e32 v136, v136
	v_mul_f32_e32 v133, v138, v133
	v_add_f32_e32 v132, 1.0, v132
	v_rcp_f32_e32 v132, v132
	v_mul_f32_e32 v135, v135, v136
	v_mul_f32_e32 v134, v134, v135
	v_add_u32_e32 v135, 0x90, v164
	v_mul_f32_e32 v131, v131, v132
	v_mul_f32_e32 v130, v130, v131
	v_cvt_pk_bf16_f32 v132, v130, v134
	v_mov_b64_e32 v[130:131], s[66:67]
	v_mad_i64_i32 v[134:135], s[14:15], v135, s97, v[130:131]
	v_lshl_add_u64 v[188:189], v[134:135], 0, v[128:129]
	v_cvt_pk_bf16_f32 v133, v133, v142
	global_store_dwordx2 v[188:189], v[132:133], off
	v_mov_b32_dpp v147, v47 row_ror:2 row_mask:0xf bank_mask:0xf
	v_mov_b32_dpp v146, v39 row_ror:2 row_mask:0xf bank_mask:0xf
	v_mov_b32_dpp v145, v47 row_ror:1 row_mask:0xf bank_mask:0xf
	v_mov_b32_dpp v147, v31 row_shr:2 row_mask:0xf bank_mask:0xf
	v_mov_b32_dpp v144, v39 row_ror:1 row_mask:0xf bank_mask:0xf
	v_mov_b32_dpp v146, v23 row_shr:2 row_mask:0xf bank_mask:0xf
	v_mov_b32_dpp v145, v31 row_shr:1 row_mask:0xf bank_mask:0xf
	v_mov_b32_dpp v144, v23 row_shr:1 row_mask:0xf bank_mask:0xf
	v_pk_fma_f32 v[146:147], v[212:213], v[146:147], v[214:215]
	v_pk_fma_f32 v[144:145], v[210:211], v[144:145], v[146:147]
	v_fmac_f32_e32 v144, v23, v208
	v_fmac_f32_e32 v145, v31, v209
	v_mul_f32_e32 v142, 0xbfb8aa3b, v145
	v_exp_f32_e32 v146, v142
	v_mov_b32_dpp v143, v46 row_ror:2 row_mask:0xf bank_mask:0xf
	v_mov_b32_dpp v142, v38 row_ror:2 row_mask:0xf bank_mask:0xf
	v_mov_b32_dpp v141, v46 row_ror:1 row_mask:0xf bank_mask:0xf
	v_mov_b32_dpp v143, v30 row_shr:2 row_mask:0xf bank_mask:0xf
	v_mov_b32_dpp v140, v38 row_ror:1 row_mask:0xf bank_mask:0xf
	v_mov_b32_dpp v142, v22 row_shr:2 row_mask:0xf bank_mask:0xf
	v_mov_b32_dpp v141, v30 row_shr:1 row_mask:0xf bank_mask:0xf
	v_mov_b32_dpp v140, v22 row_shr:1 row_mask:0xf bank_mask:0xf
	v_add_f32_e32 v146, 1.0, v146
	v_pk_fma_f32 v[142:143], v[218:219], v[142:143], v[216:217]
	v_rcp_f32_e32 v148, v146
	v_pk_fma_f32 v[140:141], v[220:221], v[140:141], v[142:143]
	v_fmac_f32_e32 v140, v22, v222
	v_fmac_f32_e32 v141, v30, v223
	v_mul_f32_e32 v142, 0xbfb8aa3b, v141
	v_exp_f32_e32 v142, v142
	v_mov_b32_dpp v139, v45 row_ror:2 row_mask:0xf bank_mask:0xf
	v_mov_b32_dpp v138, v37 row_ror:2 row_mask:0xf bank_mask:0xf
	v_mov_b32_dpp v137, v45 row_ror:1 row_mask:0xf bank_mask:0xf
	v_mov_b32_dpp v139, v29 row_shr:2 row_mask:0xf bank_mask:0xf
	v_mov_b32_dpp v136, v37 row_ror:1 row_mask:0xf bank_mask:0xf
	v_mov_b32_dpp v138, v21 row_shr:2 row_mask:0xf bank_mask:0xf
	v_mov_b32_dpp v137, v29 row_shr:1 row_mask:0xf bank_mask:0xf
	v_mov_b32_dpp v136, v21 row_shr:1 row_mask:0xf bank_mask:0xf
	v_mul_f32_e32 v143, v145, v148
	v_add_f32_e32 v142, 1.0, v142
	v_pk_fma_f32 v[138:139], v[196:197], v[138:139], v[198:199]
	v_mov_b32_dpp v135, v44 row_ror:2 row_mask:0xf bank_mask:0xf
	v_mov_b32_dpp v134, v36 row_ror:2 row_mask:0xf bank_mask:0xf
	v_mul_f32_e32 v144, v144, v143
	v_rcp_f32_e32 v145, v142
	v_pk_fma_f32 v[136:137], v[194:195], v[136:137], v[138:139]
	v_mov_b32_dpp v133, v44 row_ror:1 row_mask:0xf bank_mask:0xf
	v_mov_b32_dpp v135, v28 row_shr:2 row_mask:0xf bank_mask:0xf
	v_mov_b32_dpp v132, v36 row_ror:1 row_mask:0xf bank_mask:0xf
	v_mov_b32_dpp v134, v20 row_shr:2 row_mask:0xf bank_mask:0xf
	v_fmac_f32_e32 v136, v21, v192
	v_fmac_f32_e32 v137, v29, v193
	v_mov_b32_dpp v133, v28 row_shr:1 row_mask:0xf bank_mask:0xf
	v_mov_b32_dpp v132, v20 row_shr:1 row_mask:0xf bank_mask:0xf
	v_mul_f32_e32 v138, 0xbfb8aa3b, v137
	v_pk_fma_f32 v[134:135], v[202:203], v[134:135], v[200:201]
	v_exp_f32_e32 v142, v138
	v_pk_fma_f32 v[132:133], v[204:205], v[132:133], v[134:135]
	v_mul_f32_e32 v135, v141, v145
	v_fmac_f32_e32 v132, v20, v206
	v_fmac_f32_e32 v133, v28, v207
	v_add_f32_e32 v138, 1.0, v142
	v_mul_f32_e32 v134, 0xbfb8aa3b, v133
	v_exp_f32_e32 v134, v134
	v_rcp_f32_e32 v138, v138
	v_mul_f32_e32 v135, v140, v135
	v_add_f32_e32 v134, 1.0, v134
	v_rcp_f32_e32 v134, v134
	v_mul_f32_e32 v137, v137, v138
	v_mul_f32_e32 v136, v136, v137
	v_mul_f32_e32 v133, v133, v134
	v_mul_f32_e32 v132, v132, v133
	v_add_u32_e32 v134, 0xa0, v164
	v_cvt_pk_bf16_f32 v132, v132, v136
	v_cvt_pk_bf16_f32 v133, v135, v144
	v_mad_i64_i32 v[134:135], s[14:15], v134, s97, v[130:131]
	v_lshl_add_u64 v[190:191], v[134:135], 0, v[128:129]
	global_store_dwordx2 v[190:191], v[132:133], off
	v_mov_b32_dpp v147, v31 row_ror:2 row_mask:0xf bank_mask:0xf
	v_mov_b32_dpp v146, v23 row_ror:2 row_mask:0xf bank_mask:0xf
	v_mov_b32_dpp v145, v31 row_ror:1 row_mask:0xf bank_mask:0xf
	v_mov_b32_dpp v147, v15 row_shr:2 row_mask:0xf bank_mask:0xf
	v_mov_b32_dpp v144, v23 row_ror:1 row_mask:0xf bank_mask:0xf
; #define LAS __attribute__((address_space(3)))
; DI float frcp(float x) { return __builtin_amdgcn_rcpf(x); }
; DI u32x2 pack4(const f32x4 a) { u32x2 w; w.x = cvt_pk_bf16(a[0], a[1]); w.y = cvt_pk_bf16(a[2], a[3]); return w; }
;     DI void operator()(const pg8::f32x4 (&acc)[2][2][4][2], const pg8::Unit& u, int wr, int wc, int fr, int fq) const {
;     ...
;         const LAS float* wl = (const LAS float*)(lds + CW_OFF) + wc * 32 + 8 * fq;
; #pragma unroll
;         for (int q = 0; q < 2; ++q) {
;             const f32x4 kg0 = *(const LAS f32x4*)(wl + 4 * q), kg1 = *(const LAS f32x4*)(wl + 128 + 4 * q), kg2 = *(const LAS f32x4*)(wl + 256 + 4 * q), bg = *(const LAS f32x4*)(wl + 384 + 4 * q);
;             const f32x4 kv0 = *(const LAS f32x4*)(wl + 512 + 4 * q), kv1 = *(const LAS f32x4*)(wl + 640 + 4 * q), kv2 = *(const LAS f32x4*)(wl + 768 + 4 * q), bv = *(const LAS f32x4*)(wl + 896 + 4 * q);
; #pragma unroll
;             for (int ai = 0; ai < 2; ++ai)
; #pragma unroll
;                 for (int m = 0; m < 4; ++m) {
;                     const f32x4 cg = acc[ai][0][m][q], cv = acc[ai][1][m][q];
;                     const f32x4 pg = m > 0 ? acc[ai][0][m > 0 ? m - 1 : 0][q] : (f32x4){0.f, 0.f, 0.f, 0.f}, pv = m > 0 ? acc[ai][1][m > 0 ? m - 1 : 0][q] : (f32x4){0.f, 0.f, 0.f, 0.f};
;                     f32x4 o;
; #pragma unroll
;                     for (int e = 0; e < 4; ++e) {
;                         const float g1 = row_shift<1>(cg[e], pg[e]), g2 = row_shift<2>(cg[e], pg[e]), v1 = row_shift<1>(cv[e], pv[e]), v2 = row_shift<2>(cv[e], pv[e]);
;                         const float a = bg[e] + kg0[e] * g2 + kg1[e] * g1 + kg2[e] * cg[e], b = bv[e] + kv0[e] * v2 + kv1[e] * v1 + kv2[e] * cv[e];
;                         o[e] = a * frcp(1.f + __expf(-a)) * b;
;                     }
;                     const int r = u.pm * 256 + ai * 128 + wr * 64 + m * 16 + fr;
;                     if (m > 0 || fr >= 2) *(u32x2*)(ACT + (size_t)r * DFF + j0 + 4 * q) = pack4(o);
;                     __builtin_amdgcn_sched_barrier(0);
;                 }
	v_mov_b32_dpp v146, v7 row_shr:2 row_mask:0xf bank_mask:0xf
	v_mov_b32_dpp v145, v15 row_shr:1 row_mask:0xf bank_mask:0xf
	v_mov_b32_dpp v144, v7 row_shr:1 row_mask:0xf bank_mask:0xf
	v_pk_fma_f32 v[146:147], v[212:213], v[146:147], v[214:215]
	v_pk_fma_f32 v[144:145], v[210:211], v[144:145], v[146:147]
	v_fmac_f32_e32 v144, v7, v208
	v_fmac_f32_e32 v145, v15, v209
	v_mul_f32_e32 v142, 0xbfb8aa3b, v145
	v_exp_f32_e32 v146, v142
	v_mov_b32_dpp v143, v30 row_ror:2 row_mask:0xf bank_mask:0xf
	v_mov_b32_dpp v142, v22 row_ror:2 row_mask:0xf bank_mask:0xf
	v_mov_b32_dpp v141, v30 row_ror:1 row_mask:0xf bank_mask:0xf
	v_mov_b32_dpp v143, v14 row_shr:2 row_mask:0xf bank_mask:0xf
	v_mov_b32_dpp v140, v22 row_ror:1 row_mask:0xf bank_mask:0xf
	v_mov_b32_dpp v142, v6 row_shr:2 row_mask:0xf bank_mask:0xf
	v_mov_b32_dpp v141, v14 row_shr:1 row_mask:0xf bank_mask:0xf
	v_mov_b32_dpp v140, v6 row_shr:1 row_mask:0xf bank_mask:0xf
	v_add_f32_e32 v146, 1.0, v146
	v_pk_fma_f32 v[142:143], v[218:219], v[142:143], v[216:217]
	v_rcp_f32_e32 v148, v146
	v_pk_fma_f32 v[140:141], v[220:221], v[140:141], v[142:143]
	v_fmac_f32_e32 v140, v6, v222
	v_fmac_f32_e32 v141, v14, v223
	v_mul_f32_e32 v142, 0xbfb8aa3b, v141
	v_exp_f32_e32 v142, v142
	v_mov_b32_dpp v139, v29 row_ror:2 row_mask:0xf bank_mask:0xf
	v_mov_b32_dpp v138, v21 row_ror:2 row_mask:0xf bank_mask:0xf
	v_mov_b32_dpp v137, v29 row_ror:1 row_mask:0xf bank_mask:0xf
	v_mov_b32_dpp v139, v13 row_shr:2 row_mask:0xf bank_mask:0xf
	v_mov_b32_dpp v136, v21 row_ror:1 row_mask:0xf bank_mask:0xf
	v_mov_b32_dpp v138, v5 row_shr:2 row_mask:0xf bank_mask:0xf
	v_mov_b32_dpp v137, v13 row_shr:1 row_mask:0xf bank_mask:0xf
	v_mov_b32_dpp v136, v5 row_shr:1 row_mask:0xf bank_mask:0xf
	v_mul_f32_e32 v143, v145, v148
	v_add_f32_e32 v142, 1.0, v142
	v_pk_fma_f32 v[138:139], v[196:197], v[138:139], v[198:199]
	v_mov_b32_dpp v135, v28 row_ror:2 row_mask:0xf bank_mask:0xf
	v_mov_b32_dpp v134, v20 row_ror:2 row_mask:0xf bank_mask:0xf
	v_mul_f32_e32 v144, v144, v143
	v_rcp_f32_e32 v145, v142
	v_pk_fma_f32 v[136:137], v[194:195], v[136:137], v[138:139]
	v_mov_b32_dpp v133, v28 row_ror:1 row_mask:0xf bank_mask:0xf
	v_mov_b32_dpp v135, v12 row_shr:2 row_mask:0xf bank_mask:0xf
	v_mov_b32_dpp v132, v20 row_ror:1 row_mask:0xf bank_mask:0xf
	v_mov_b32_dpp v134, v4 row_shr:2 row_mask:0xf bank_mask:0xf
	v_fmac_f32_e32 v136, v5, v192
	v_fmac_f32_e32 v137, v13, v193
	v_mov_b32_dpp v133, v12 row_shr:1 row_mask:0xf bank_mask:0xf
	v_mov_b32_dpp v132, v4 row_shr:1 row_mask:0xf bank_mask:0xf
	v_mul_f32_e32 v138, 0xbfb8aa3b, v137
	v_pk_fma_f32 v[134:135], v[202:203], v[134:135], v[200:201]
	v_exp_f32_e32 v142, v138
	v_pk_fma_f32 v[132:133], v[204:205], v[132:133], v[134:135]
	v_mul_f32_e32 v135, v141, v145
	v_fmac_f32_e32 v132, v4, v206
	v_fmac_f32_e32 v133, v12, v207
	v_add_f32_e32 v138, 1.0, v142
	v_mul_f32_e32 v134, 0xbfb8aa3b, v133
	v_exp_f32_e32 v134, v134
	v_rcp_f32_e32 v138, v138
	v_mad_i64_i32 v[130:131], s[14:15], v165, s97, v[130:131]
	v_add_f32_e32 v134, 1.0, v134
	v_rcp_f32_e32 v134, v134
	v_mul_f32_e32 v137, v137, v138
	v_mul_f32_e32 v135, v140, v135
	v_mul_f32_e32 v136, v136, v137
	v_mul_f32_e32 v133, v133, v134
	v_mul_f32_e32 v132, v132, v133
	v_lshl_add_u64 v[192:193], v[130:131], 0, v[128:129]
	v_cvt_pk_bf16_f32 v132, v132, v136
	v_cvt_pk_bf16_f32 v133, v135, v144
	global_store_dwordx2 v[192:193], v[132:133], off
	ds_read_b128 v[148:151], v160 offset:16
	ds_read_b128 v[152:155], v160 offset:528
	ds_read_b128 v[156:159], v160 offset:1040
	ds_read_b128 v[144:147], v160 offset:1552
	ds_read_b128 v[128:131], v160 offset:2064
	ds_read_b128 v[132:135], v160 offset:2576
	ds_read_b128 v[140:143], v160 offset:3088
	ds_read_b128 v[136:139], v160 offset:3600
	v_mov_b32_e32 v236, v161
	v_mov_b32_e32 v240, v161
	s_waitcnt lgkmcnt(4)
	v_mov_b32_e32 v203, v144
	v_mov_b32_dpp v236, v236 row_ror:1 row_mask:0xf bank_mask:0xf
	v_mov_b32_dpp v240, v240 row_ror:2 row_mask:0xf bank_mask:0xf
	v_mov_b32_e32 v227, v236
	v_mov_b32_e32 v229, v240
	v_mov_b32_e32 v226, v236
	v_mov_b32_e32 v228, v240
	v_mov_b32_e32 v231, v236
	v_mov_b32_e32 v233, v240
	v_mov_b32_e32 v230, v236
	v_mov_b32_e32 v232, v240
	v_mov_b32_e32 v235, v236
	v_mov_b32_e32 v239, v240
	v_mov_b32_e32 v234, v236
	v_mov_b32_e32 v238, v240
	v_mov_b32_e32 v237, v236
	v_mov_b32_e32 v241, v240
	v_mov_b32_dpp v227, v120 row_shr:1 row_mask:0xf bank_mask:0xf
	v_mov_b32_dpp v229, v120 row_shr:2 row_mask:0xf bank_mask:0xf
	v_mov_b32_dpp v226, v112 row_shr:1 row_mask:0xf bank_mask:0xf
	v_mov_b32_dpp v228, v112 row_shr:2 row_mask:0xf bank_mask:0xf
	v_mov_b32_dpp v231, v121 row_shr:1 row_mask:0xf bank_mask:0xf
	v_mov_b32_dpp v233, v121 row_shr:2 row_mask:0xf bank_mask:0xf
	v_mov_b32_dpp v230, v113 row_shr:1 row_mask:0xf bank_mask:0xf
	v_mov_b32_dpp v232, v113 row_shr:2 row_mask:0xf bank_mask:0xf
	v_mov_b32_dpp v235, v122 row_shr:1 row_mask:0xf bank_mask:0xf
	v_mov_b32_dpp v239, v122 row_shr:2 row_mask:0xf bank_mask:0xf
	v_mov_b32_dpp v234, v114 row_shr:1 row_mask:0xf bank_mask:0xf
	v_mov_b32_dpp v238, v114 row_shr:2 row_mask:0xf bank_mask:0xf
	v_mov_b32_dpp v237, v123 row_shr:1 row_mask:0xf bank_mask:0xf
	v_mov_b32_dpp v241, v123 row_shr:2 row_mask:0xf bank_mask:0xf
	v_mov_b32_dpp v236, v115 row_shr:1 row_mask:0xf bank_mask:0xf
	v_mov_b32_dpp v240, v115 row_shr:2 row_mask:0xf bank_mask:0xf
	s_waitcnt lgkmcnt(0)
	v_mov_b32_e32 v202, v136
	v_mov_b32_e32 v204, v128
	v_mov_b32_e32 v205, v148
	v_mov_b32_e32 v206, v132
	v_mov_b32_e32 v207, v152
	v_mov_b32_e32 v208, v140
	v_mov_b32_e32 v209, v156
	v_mov_b32_e32 v200, v137
	v_mov_b32_e32 v201, v145
	v_mov_b32_e32 v198, v129
	v_mov_b32_e32 v199, v149
	v_mov_b32_e32 v196, v133
	v_mov_b32_e32 v197, v153
	v_mov_b32_e32 v194, v141
	v_mov_b32_e32 v195, v157
	v_mov_b32_e32 v218, v138
	v_mov_b32_e32 v219, v146
	v_mov_b32_e32 v220, v130
	v_mov_b32_e32 v221, v150
	v_mov_b32_e32 v222, v134
	v_mov_b32_e32 v223, v154
	v_mov_b32_e32 v224, v142
	v_mov_b32_e32 v225, v158
	v_mov_b32_e32 v216, v139
	v_mov_b32_e32 v217, v147
	v_mov_b32_e32 v214, v131
	v_mov_b32_e32 v215, v151
	v_mov_b32_e32 v212, v135
	v_mov_b32_e32 v213, v155
	v_mov_b32_e32 v210, v143
	v_mov_b32_e32 v211, v159
	s_and_saveexec_b64 s[14:15], s[38:39]
	s_xor_b64 s[38:39], exec, s[14:15]
	s_cbranch_execz .LBB0_836
; #define LAS __attribute__((address_space(3)))
;     DI void operator()(const pg8::f32x4 (&acc)[2][2][4][2], const pg8::Unit& u, int wr, int wc, int fr, int fq) const {
;     ...
;         const LAS float* wl = (const LAS float*)(lds + CW_OFF) + wc * 32 + 8 * fq;
; #pragma unroll
;         for (int q = 0; q < 2; ++q) {
;             const f32x4 kg0 = *(const LAS f32x4*)(wl + 4 * q), kg1 = *(const LAS f32x4*)(wl + 128 + 4 * q), kg2 = *(const LAS f32x4*)(wl + 256 + 4 * q), bg = *(const LAS f32x4*)(wl + 384 + 4 * q);
;             const f32x4 kv0 = *(const LAS f32x4*)(wl + 512 + 4 * q), kv1 = *(const LAS f32x4*)(wl + 640 + 4 * q), kv2 = *(const LAS f32x4*)(wl + 768 + 4 * q), bv = *(const LAS f32x4*)(wl + 896 + 4 * q);
	v_mov_b32_e32 v210, v143
	v_mov_b32_e32 v212, v135
	v_mov_b32_e32 v214, v131
	v_mov_b32_e32 v216, v139
	v_mov_b32_e32 v143, v158
	v_mov_b32_e32 v135, v154
	v_mov_b32_e32 v131, v150
	v_mov_b32_e32 v139, v146
	v_mov_b32_e32 v194, v141
	v_mov_b32_e32 v196, v133
	v_mov_b32_e32 v198, v129
	v_mov_b32_e32 v200, v137
	v_mov_b32_e32 v141, v156
	v_mov_b32_e32 v133, v152
	v_mov_b32_e32 v129, v148
	v_mov_b32_e32 v137, v144
	v_mov_b32_e32 v211, v159
	v_mov_b32_e32 v213, v155
	v_mov_b32_e32 v215, v151
	v_mov_b32_e32 v217, v147
	v_mov_b32_e32 v195, v157
	v_mov_b32_e32 v197, v153
	v_mov_b32_e32 v199, v149
	v_mov_b32_e32 v201, v145
	v_mov_b64_e32 v[224:225], v[142:143]
	v_mov_b64_e32 v[222:223], v[134:135]
	v_mov_b64_e32 v[220:221], v[130:131]
	v_mov_b64_e32 v[218:219], v[138:139]
	v_mov_b64_e32 v[208:209], v[140:141]
	v_mov_b64_e32 v[206:207], v[132:133]
	v_mov_b64_e32 v[204:205], v[128:129]
	v_mov_b64_e32 v[202:203], v[136:137]

; DI float frcp(float x) { return __builtin_amdgcn_rcpf(x); }
; DI u32x2 pack4(const f32x4 a) { u32x2 w; w.x = cvt_pk_bf16(a[0], a[1]); w.y = cvt_pk_bf16(a[2], a[3]); return w; }
;     DI void operator()(const pg8::f32x4 (&acc)[2][2][4][2], const pg8::Unit& u, int wr, int wc, int fr, int fq) const {
;     ...
;                 for (int m = 0; m < 4; ++m) {
;                     const f32x4 cg = acc[ai][0][m][q], cv = acc[ai][1][m][q];
;                     const f32x4 pg = m > 0 ? acc[ai][0][m > 0 ? m - 1 : 0][q] : (f32x4){0.f, 0.f, 0.f, 0.f}, pv = m > 0 ? acc[ai][1][m > 0 ? m - 1 : 0][q] : (f32x4){0.f, 0.f, 0.f, 0.f};
;                     f32x4 o;
; #pragma unroll
;                     for (int e = 0; e < 4; ++e) {
;                         const float g1 = row_shift<1>(cg[e], pg[e]), g2 = row_shift<2>(cg[e], pg[e]), v1 = row_shift<1>(cv[e], pv[e]), v2 = row_shift<2>(cv[e], pv[e]);
;                         const float a = bg[e] + kg0[e] * g2 + kg1[e] * g1 + kg2[e] * cg[e], b = bv[e] + kv0[e] * v2 + kv1[e] * v1 + kv2[e] * cv[e];
;                         o[e] = a * frcp(1.f + __expf(-a)) * b;
;                     }
;                     const int r = u.pm * 256 + ai * 128 + wr * 64 + m * 16 + fr;
;                     if (m > 0 || fr >= 2) *(u32x2*)(ACT + (size_t)r * DFF + j0 + 4 * q) = pack4(o);
;                     __builtin_amdgcn_sched_barrier(0);
;                 }
.LBB0_838:
	s_or_b64 exec, exec, s[38:39]
	v_mov_b32_dpp v143, v123 row_ror:2 row_mask:0xf bank_mask:0xf
	v_mov_b32_dpp v142, v115 row_ror:2 row_mask:0xf bank_mask:0xf
	v_mov_b32_dpp v141, v123 row_ror:1 row_mask:0xf bank_mask:0xf
	v_mov_b32_dpp v143, v107 row_shr:2 row_mask:0xf bank_mask:0xf
	v_mov_b32_dpp v140, v115 row_ror:1 row_mask:0xf bank_mask:0xf
	v_mov_b32_dpp v142, v99 row_shr:2 row_mask:0xf bank_mask:0xf
	v_mov_b32_dpp v141, v107 row_shr:1 row_mask:0xf bank_mask:0xf
	v_mov_b32_dpp v140, v99 row_shr:1 row_mask:0xf bank_mask:0xf
	v_pk_fma_f32 v[142:143], v[214:215], v[142:143], v[216:217]
	v_pk_fma_f32 v[140:141], v[212:213], v[140:141], v[142:143]
	v_fmac_f32_e32 v140, v99, v210
	v_fmac_f32_e32 v141, v107, v211
	v_mul_f32_e32 v138, 0xbfb8aa3b, v141
	v_exp_f32_e32 v142, v138
	v_mov_b32_dpp v139, v122 row_ror:2 row_mask:0xf bank_mask:0xf
	v_mov_b32_dpp v138, v114 row_ror:2 row_mask:0xf bank_mask:0xf
	v_mov_b32_dpp v137, v122 row_ror:1 row_mask:0xf bank_mask:0xf
	v_mov_b32_dpp v139, v106 row_shr:2 row_mask:0xf bank_mask:0xf
	v_mov_b32_dpp v136, v114 row_ror:1 row_mask:0xf bank_mask:0xf
	v_mov_b32_dpp v138, v98 row_shr:2 row_mask:0xf bank_mask:0xf
	v_mov_b32_dpp v137, v106 row_shr:1 row_mask:0xf bank_mask:0xf
	v_mov_b32_dpp v136, v98 row_shr:1 row_mask:0xf bank_mask:0xf
	v_add_f32_e32 v142, 1.0, v142
	v_pk_fma_f32 v[138:139], v[220:221], v[138:139], v[218:219]
	v_rcp_f32_e32 v144, v142
	v_pk_fma_f32 v[136:137], v[222:223], v[136:137], v[138:139]
	v_fmac_f32_e32 v136, v98, v224
	v_fmac_f32_e32 v137, v106, v225
	v_mul_f32_e32 v138, 0xbfb8aa3b, v137
	v_exp_f32_e32 v138, v138
	v_mov_b32_dpp v135, v121 row_ror:2 row_mask:0xf bank_mask:0xf
	v_mov_b32_dpp v134, v113 row_ror:2 row_mask:0xf bank_mask:0xf
	v_mov_b32_dpp v133, v121 row_ror:1 row_mask:0xf bank_mask:0xf
	v_mov_b32_dpp v135, v105 row_shr:2 row_mask:0xf bank_mask:0xf
	v_mov_b32_dpp v132, v113 row_ror:1 row_mask:0xf bank_mask:0xf
	v_mov_b32_dpp v134, v97 row_shr:2 row_mask:0xf bank_mask:0xf
	v_mov_b32_dpp v133, v105 row_shr:1 row_mask:0xf bank_mask:0xf
	v_mov_b32_dpp v132, v97 row_shr:1 row_mask:0xf bank_mask:0xf
	v_mul_f32_e32 v139, v141, v144
	v_add_f32_e32 v138, 1.0, v138
	v_pk_fma_f32 v[134:135], v[198:199], v[134:135], v[200:201]
	v_mov_b32_dpp v131, v120 row_ror:2 row_mask:0xf bank_mask:0xf
	v_mov_b32_dpp v130, v112 row_ror:2 row_mask:0xf bank_mask:0xf
	v_mul_f32_e32 v140, v140, v139
	v_rcp_f32_e32 v141, v138
	v_pk_fma_f32 v[132:133], v[196:197], v[132:133], v[134:135]
	v_mov_b32_dpp v129, v120 row_ror:1 row_mask:0xf bank_mask:0xf
	v_mov_b32_dpp v131, v104 row_shr:2 row_mask:0xf bank_mask:0xf
	v_mov_b32_dpp v128, v112 row_ror:1 row_mask:0xf bank_mask:0xf
	v_mov_b32_dpp v130, v96 row_shr:2 row_mask:0xf bank_mask:0xf
	v_fmac_f32_e32 v132, v97, v194
	v_fmac_f32_e32 v133, v105, v195
	v_mov_b32_dpp v129, v104 row_shr:1 row_mask:0xf bank_mask:0xf
	v_mov_b32_dpp v128, v96 row_shr:1 row_mask:0xf bank_mask:0xf
	v_mul_f32_e32 v134, 0xbfb8aa3b, v133
	v_pk_fma_f32 v[130:131], v[204:205], v[130:131], v[202:203]
	v_exp_f32_e32 v138, v134
	v_pk_fma_f32 v[128:129], v[206:207], v[128:129], v[130:131]
	v_mul_f32_e32 v131, v137, v141
	v_fmac_f32_e32 v128, v96, v208
	v_fmac_f32_e32 v129, v104, v209
	v_add_f32_e32 v134, 1.0, v138
	v_mul_f32_e32 v130, 0xbfb8aa3b, v129
	v_exp_f32_e32 v130, v130
	v_rcp_f32_e32 v134, v134
	v_mul_f32_e32 v131, v136, v131
	v_add_f32_e32 v130, 1.0, v130
	v_rcp_f32_e32 v130, v130
	v_mul_f32_e32 v133, v133, v134
	v_mul_f32_e32 v132, v132, v133
	v_mul_f32_e32 v129, v129, v130
	v_mul_f32_e32 v128, v128, v129
	v_cvt_pk_bf16_f32 v128, v128, v132
	v_cvt_pk_bf16_f32 v129, v131, v140
	global_store_dwordx2 v[182:183], v[128:129], off offset:8
	v_mov_b32_dpp v143, v107 row_ror:2 row_mask:0xf bank_mask:0xf
	v_mov_b32_dpp v142, v99 row_ror:2 row_mask:0xf bank_mask:0xf
	v_mov_b32_dpp v141, v107 row_ror:1 row_mask:0xf bank_mask:0xf
	v_mov_b32_dpp v143, v91 row_shr:2 row_mask:0xf bank_mask:0xf
	v_mov_b32_dpp v140, v99 row_ror:1 row_mask:0xf bank_mask:0xf
	v_mov_b32_dpp v142, v83 row_shr:2 row_mask:0xf bank_mask:0xf
	v_mov_b32_dpp v141, v91 row_shr:1 row_mask:0xf bank_mask:0xf
	v_mov_b32_dpp v140, v83 row_shr:1 row_mask:0xf bank_mask:0xf
	v_pk_fma_f32 v[142:143], v[214:215], v[142:143], v[216:217]
	v_pk_fma_f32 v[140:141], v[212:213], v[140:141], v[142:143]
	v_fmac_f32_e32 v140, v83, v210
	v_fmac_f32_e32 v141, v91, v211
	v_mul_f32_e32 v138, 0xbfb8aa3b, v141
	v_exp_f32_e32 v142, v138
	v_mov_b32_dpp v139, v106 row_ror:2 row_mask:0xf bank_mask:0xf
	v_mov_b32_dpp v138, v98 row_ror:2 row_mask:0xf bank_mask:0xf
	v_mov_b32_dpp v137, v106 row_ror:1 row_mask:0xf bank_mask:0xf
	v_mov_b32_dpp v139, v90 row_shr:2 row_mask:0xf bank_mask:0xf
	v_mov_b32_dpp v136, v98 row_ror:1 row_mask:0xf bank_mask:0xf
	v_mov_b32_dpp v138, v82 row_shr:2 row_mask:0xf bank_mask:0xf
	v_mov_b32_dpp v137, v90 row_shr:1 row_mask:0xf bank_mask:0xf
	v_mov_b32_dpp v136, v82 row_shr:1 row_mask:0xf bank_mask:0xf
	v_add_f32_e32 v142, 1.0, v142
	v_pk_fma_f32 v[138:139], v[220:221], v[138:139], v[218:219]
	v_rcp_f32_e32 v144, v142
	v_pk_fma_f32 v[136:137], v[222:223], v[136:137], v[138:139]
	v_fmac_f32_e32 v136, v82, v224
	v_fmac_f32_e32 v137, v90, v225
	v_mul_f32_e32 v138, 0xbfb8aa3b, v137
	v_exp_f32_e32 v138, v138
	v_mov_b32_dpp v135, v105 row_ror:2 row_mask:0xf bank_mask:0xf
	v_mov_b32_dpp v134, v97 row_ror:2 row_mask:0xf bank_mask:0xf
	v_mov_b32_dpp v133, v105 row_ror:1 row_mask:0xf bank_mask:0xf
	v_mov_b32_dpp v135, v89 row_shr:2 row_mask:0xf bank_mask:0xf
	v_mov_b32_dpp v132, v97 row_ror:1 row_mask:0xf bank_mask:0xf
	v_mov_b32_dpp v134, v81 row_shr:2 row_mask:0xf bank_mask:0xf
	v_mov_b32_dpp v133, v89 row_shr:1 row_mask:0xf bank_mask:0xf
; DI float frcp(float x) { return __builtin_amdgcn_rcpf(x); }
; DI u32x2 pack4(const f32x4 a) { u32x2 w; w.x = cvt_pk_bf16(a[0], a[1]); w.y = cvt_pk_bf16(a[2], a[3]); return w; }
;     DI void operator()(const pg8::f32x4 (&acc)[2][2][4][2], const pg8::Unit& u, int wr, int wc, int fr, int fq) const {
;     ...
;                 for (int m = 0; m < 4; ++m) {
;                     const f32x4 cg = acc[ai][0][m][q], cv = acc[ai][1][m][q];
;                     const f32x4 pg = m > 0 ? acc[ai][0][m > 0 ? m - 1 : 0][q] : (f32x4){0.f, 0.f, 0.f, 0.f}, pv = m > 0 ? acc[ai][1][m > 0 ? m - 1 : 0][q] : (f32x4){0.f, 0.f, 0.f, 0.f};
;                     f32x4 o;
; #pragma unroll
;                     for (int e = 0; e < 4; ++e) {
;                         const float g1 = row_shift<1>(cg[e], pg[e]), g2 = row_shift<2>(cg[e], pg[e]), v1 = row_shift<1>(cv[e], pv[e]), v2 = row_shift<2>(cv[e], pv[e]);
;                         const float a = bg[e] + kg0[e] * g2 + kg1[e] * g1 + kg2[e] * cg[e], b = bv[e] + kv0[e] * v2 + kv1[e] * v1 + kv2[e] * cv[e];
;                         o[e] = a * frcp(1.f + __expf(-a)) * b;
;                     }
;                     const int r = u.pm * 256 + ai * 128 + wr * 64 + m * 16 + fr;
;                     if (m > 0 || fr >= 2) *(u32x2*)(ACT + (size_t)r * DFF + j0 + 4 * q) = pack4(o);
;                     __builtin_amdgcn_sched_barrier(0);
;                 }
	v_mov_b32_dpp v132, v81 row_shr:1 row_mask:0xf bank_mask:0xf
	v_mul_f32_e32 v139, v141, v144
	v_add_f32_e32 v138, 1.0, v138
	v_pk_fma_f32 v[134:135], v[198:199], v[134:135], v[200:201]
	v_mov_b32_dpp v131, v104 row_ror:2 row_mask:0xf bank_mask:0xf
	v_mov_b32_dpp v130, v96 row_ror:2 row_mask:0xf bank_mask:0xf
	v_mul_f32_e32 v140, v140, v139
	v_rcp_f32_e32 v141, v138
	v_pk_fma_f32 v[132:133], v[196:197], v[132:133], v[134:135]
	v_mov_b32_dpp v129, v104 row_ror:1 row_mask:0xf bank_mask:0xf
	v_mov_b32_dpp v131, v88 row_shr:2 row_mask:0xf bank_mask:0xf
	v_mov_b32_dpp v128, v96 row_ror:1 row_mask:0xf bank_mask:0xf
	v_mov_b32_dpp v130, v80 row_shr:2 row_mask:0xf bank_mask:0xf
	v_fmac_f32_e32 v132, v81, v194
	v_fmac_f32_e32 v133, v89, v195
	v_mov_b32_dpp v129, v88 row_shr:1 row_mask:0xf bank_mask:0xf
	v_mov_b32_dpp v128, v80 row_shr:1 row_mask:0xf bank_mask:0xf
	v_mul_f32_e32 v134, 0xbfb8aa3b, v133
	v_pk_fma_f32 v[130:131], v[204:205], v[130:131], v[202:203]
	v_exp_f32_e32 v138, v134
	v_pk_fma_f32 v[128:129], v[206:207], v[128:129], v[130:131]
	v_mul_f32_e32 v131, v137, v141
	v_fmac_f32_e32 v128, v80, v208
	v_fmac_f32_e32 v129, v88, v209
	v_add_f32_e32 v134, 1.0, v138
	v_mul_f32_e32 v130, 0xbfb8aa3b, v129
	v_exp_f32_e32 v130, v130
	v_rcp_f32_e32 v134, v134
	v_mul_f32_e32 v131, v136, v131
	v_add_f32_e32 v130, 1.0, v130
	v_rcp_f32_e32 v130, v130
	v_mul_f32_e32 v133, v133, v134
	v_mul_f32_e32 v132, v132, v133
	v_mul_f32_e32 v129, v129, v130
	v_mul_f32_e32 v128, v128, v129
	v_cvt_pk_bf16_f32 v128, v128, v132
	v_cvt_pk_bf16_f32 v129, v131, v140
	global_store_dwordx2 v[184:185], v[128:129], off offset:8
	v_mov_b32_dpp v143, v91 row_ror:2 row_mask:0xf bank_mask:0xf
	v_mov_b32_dpp v142, v83 row_ror:2 row_mask:0xf bank_mask:0xf
	v_mov_b32_dpp v141, v91 row_ror:1 row_mask:0xf bank_mask:0xf
	v_mov_b32_dpp v143, v75 row_shr:2 row_mask:0xf bank_mask:0xf
	v_mov_b32_dpp v140, v83 row_ror:1 row_mask:0xf bank_mask:0xf
	v_mov_b32_dpp v142, v67 row_shr:2 row_mask:0xf bank_mask:0xf
	v_mov_b32_dpp v141, v75 row_shr:1 row_mask:0xf bank_mask:0xf
	v_mov_b32_dpp v140, v67 row_shr:1 row_mask:0xf bank_mask:0xf
	v_pk_fma_f32 v[142:143], v[214:215], v[142:143], v[216:217]
	v_pk_fma_f32 v[140:141], v[212:213], v[140:141], v[142:143]
	v_fmac_f32_e32 v140, v67, v210
	v_fmac_f32_e32 v141, v75, v211
	v_mul_f32_e32 v138, 0xbfb8aa3b, v141
	v_exp_f32_e32 v142, v138
	v_mov_b32_dpp v139, v90 row_ror:2 row_mask:0xf bank_mask:0xf
	v_mov_b32_dpp v138, v82 row_ror:2 row_mask:0xf bank_mask:0xf
	v_mov_b32_dpp v137, v90 row_ror:1 row_mask:0xf bank_mask:0xf
	v_mov_b32_dpp v139, v74 row_shr:2 row_mask:0xf bank_mask:0xf
	v_mov_b32_dpp v136, v82 row_ror:1 row_mask:0xf bank_mask:0xf
	v_mov_b32_dpp v138, v66 row_shr:2 row_mask:0xf bank_mask:0xf
	v_mov_b32_dpp v137, v74 row_shr:1 row_mask:0xf bank_mask:0xf
	v_mov_b32_dpp v136, v66 row_shr:1 row_mask:0xf bank_mask:0xf
	v_add_f32_e32 v142, 1.0, v142
	v_pk_fma_f32 v[138:139], v[220:221], v[138:139], v[218:219]
	v_rcp_f32_e32 v144, v142
	v_pk_fma_f32 v[136:137], v[222:223], v[136:137], v[138:139]
	v_fmac_f32_e32 v136, v66, v224
	v_fmac_f32_e32 v137, v74, v225
	v_mul_f32_e32 v138, 0xbfb8aa3b, v137
	v_exp_f32_e32 v138, v138
	v_mov_b32_dpp v135, v89 row_ror:2 row_mask:0xf bank_mask:0xf
	v_mov_b32_dpp v134, v81 row_ror:2 row_mask:0xf bank_mask:0xf
	v_mov_b32_dpp v133, v89 row_ror:1 row_mask:0xf bank_mask:0xf
	v_mov_b32_dpp v135, v73 row_shr:2 row_mask:0xf bank_mask:0xf
	v_mov_b32_dpp v132, v81 row_ror:1 row_mask:0xf bank_mask:0xf
	v_mov_b32_dpp v134, v65 row_shr:2 row_mask:0xf bank_mask:0xf
	v_mov_b32_dpp v133, v73 row_shr:1 row_mask:0xf bank_mask:0xf
	v_mov_b32_dpp v132, v65 row_shr:1 row_mask:0xf bank_mask:0xf
	v_mul_f32_e32 v139, v141, v144
	v_add_f32_e32 v138, 1.0, v138
	v_pk_fma_f32 v[134:135], v[198:199], v[134:135], v[200:201]
	v_mov_b32_dpp v131, v88 row_ror:2 row_mask:0xf bank_mask:0xf
	v_mov_b32_dpp v130, v80 row_ror:2 row_mask:0xf bank_mask:0xf
	v_mul_f32_e32 v140, v140, v139
	v_rcp_f32_e32 v141, v138
	v_pk_fma_f32 v[132:133], v[196:197], v[132:133], v[134:135]
	v_mov_b32_dpp v129, v88 row_ror:1 row_mask:0xf bank_mask:0xf
	v_mov_b32_dpp v131, v72 row_shr:2 row_mask:0xf bank_mask:0xf
	v_mov_b32_dpp v128, v80 row_ror:1 row_mask:0xf bank_mask:0xf
	v_mov_b32_dpp v130, v64 row_shr:2 row_mask:0xf bank_mask:0xf
	v_fmac_f32_e32 v132, v65, v194
	v_fmac_f32_e32 v133, v73, v195
	v_mov_b32_dpp v129, v72 row_shr:1 row_mask:0xf bank_mask:0xf
	v_mov_b32_dpp v128, v64 row_shr:1 row_mask:0xf bank_mask:0xf
	v_mul_f32_e32 v134, 0xbfb8aa3b, v133
	v_pk_fma_f32 v[130:131], v[204:205], v[130:131], v[202:203]
	v_exp_f32_e32 v138, v134
	v_pk_fma_f32 v[128:129], v[206:207], v[128:129], v[130:131]
	v_mul_f32_e32 v131, v137, v141
	v_fmac_f32_e32 v128, v64, v208
	v_fmac_f32_e32 v129, v72, v209
	v_add_f32_e32 v134, 1.0, v138
	v_mul_f32_e32 v130, 0xbfb8aa3b, v129
	v_exp_f32_e32 v130, v130
	v_rcp_f32_e32 v134, v134
	v_mul_f32_e32 v131, v136, v131
	v_add_f32_e32 v130, 1.0, v130
	v_rcp_f32_e32 v130, v130
	v_mul_f32_e32 v133, v133, v134
	v_mul_f32_e32 v132, v132, v133
	v_mul_f32_e32 v129, v129, v130
	v_mul_f32_e32 v128, v128, v129
	v_cvt_pk_bf16_f32 v128, v128, v132
	v_cvt_pk_bf16_f32 v129, v131, v140
	global_store_dwordx2 v[186:187], v[128:129], off offset:8
	v_mov_b32_e32 v136, v161
	v_mov_b32_e32 v142, v161
	s_nop 0
	v_mov_b32_dpp v136, v136 row_ror:1 row_mask:0xf bank_mask:0xf
	v_mov_b32_dpp v142, v142 row_ror:2 row_mask:0xf bank_mask:0xf
	v_mov_b32_e32 v129, v136
	v_mov_b32_e32 v131, v142
	v_mov_b32_e32 v128, v136
	v_mov_b32_e32 v130, v142
	v_mov_b32_e32 v133, v136
	v_mov_b32_e32 v135, v142
	v_mov_b32_e32 v132, v136
	v_mov_b32_e32 v134, v142
	v_mov_b32_e32 v139, v136
	v_mov_b32_e32 v141, v142
	v_mov_b32_e32 v138, v136
	v_mov_b32_e32 v140, v142
	v_mov_b32_e32 v137, v136
	v_mov_b32_e32 v143, v142
	v_mov_b32_dpp v129, v56 row_shr:1 row_mask:0xf bank_mask:0xf
	v_mov_b32_dpp v131, v56 row_shr:2 row_mask:0xf bank_mask:0xf
	v_mov_b32_dpp v128, v48 row_shr:1 row_mask:0xf bank_mask:0xf
	v_mov_b32_dpp v130, v48 row_shr:2 row_mask:0xf bank_mask:0xf
	v_mov_b32_dpp v133, v57 row_shr:1 row_mask:0xf bank_mask:0xf
	v_mov_b32_dpp v135, v57 row_shr:2 row_mask:0xf bank_mask:0xf
	v_mov_b32_dpp v132, v49 row_shr:1 row_mask:0xf bank_mask:0xf
	v_mov_b32_dpp v134, v49 row_shr:2 row_mask:0xf bank_mask:0xf
	v_mov_b32_dpp v139, v58 row_shr:1 row_mask:0xf bank_mask:0xf
	v_mov_b32_dpp v141, v58 row_shr:2 row_mask:0xf bank_mask:0xf
	v_mov_b32_dpp v138, v50 row_shr:1 row_mask:0xf bank_mask:0xf
	v_mov_b32_dpp v140, v50 row_shr:2 row_mask:0xf bank_mask:0xf
	v_mov_b32_dpp v137, v59 row_shr:1 row_mask:0xf bank_mask:0xf
	v_mov_b32_dpp v143, v59 row_shr:2 row_mask:0xf bank_mask:0xf
	v_mov_b32_dpp v136, v51 row_shr:1 row_mask:0xf bank_mask:0xf
	v_mov_b32_dpp v142, v51 row_shr:2 row_mask:0xf bank_mask:0xf
	s_and_saveexec_b64 s[38:39], vcc
	s_cbranch_execz .LBB0_840
; DI float frcp(float x) { return __builtin_amdgcn_rcpf(x); }
; DI u32x2 pack4(const f32x4 a) { u32x2 w; w.x = cvt_pk_bf16(a[0], a[1]); w.y = cvt_pk_bf16(a[2], a[3]); return w; }
;     DI void operator()(const pg8::f32x4 (&acc)[2][2][4][2], const pg8::Unit& u, int wr, int wc, int fr, int fq) const {
;     ...
;                 for (int m = 0; m < 4; ++m) {
;                     const f32x4 cg = acc[ai][0][m][q], cv = acc[ai][1][m][q];
;                     const f32x4 pg = m > 0 ? acc[ai][0][m > 0 ? m - 1 : 0][q] : (f32x4){0.f, 0.f, 0.f, 0.f}, pv = m > 0 ? acc[ai][1][m > 0 ? m - 1 : 0][q] : (f32x4){0.f, 0.f, 0.f, 0.f};
;                     f32x4 o;
; #pragma unroll
;                     for (int e = 0; e < 4; ++e) {
;                         const float g1 = row_shift<1>(cg[e], pg[e]), g2 = row_shift<2>(cg[e], pg[e]), v1 = row_shift<1>(cv[e], pv[e]), v2 = row_shift<2>(cv[e], pv[e]);
;                         const float a = bg[e] + kg0[e] * g2 + kg1[e] * g1 + kg2[e] * cg[e], b = bv[e] + kv0[e] * v2 + kv1[e] * v1 + kv2[e] * cv[e];
;                         o[e] = a * frcp(1.f + __expf(-a)) * b;
;                     }
;                     const int r = u.pm * 256 + ai * 128 + wr * 64 + m * 16 + fr;
;                     if (m > 0 || fr >= 2) *(u32x2*)(ACT + (size_t)r * DFF + j0 + 4 * q) = pack4(o);
;                     __builtin_amdgcn_sched_barrier(0);
;                 }
	v_pk_fma_f32 v[142:143], v[214:215], v[142:143], v[216:217]
	v_pk_fma_f32 v[136:137], v[212:213], v[136:137], v[142:143]
	v_pk_fma_f32 v[140:141], v[220:221], v[140:141], v[218:219]
	v_fmac_f32_e32 v136, v51, v210
	v_fmac_f32_e32 v137, v59, v211
	v_pk_fma_f32 v[138:139], v[222:223], v[138:139], v[140:141]
	v_mul_f32_e32 v142, 0xbfb8aa3b, v137
	v_exp_f32_e32 v143, v142
	v_pk_fma_f32 v[134:135], v[198:199], v[134:135], v[200:201]
	v_pk_fma_f32 v[130:131], v[204:205], v[130:131], v[202:203]
	v_add_f32_e32 v143, 1.0, v143
	v_rcp_f32_e32 v144, v143
	v_fmac_f32_e32 v138, v50, v224
	v_fmac_f32_e32 v139, v58, v225
	v_pk_fma_f32 v[132:133], v[196:197], v[132:133], v[134:135]
	v_mul_f32_e32 v140, 0xbfb8aa3b, v139
	v_exp_f32_e32 v140, v140
	v_mul_f32_e32 v137, v137, v144
	v_mul_f32_e32 v141, v136, v137
	v_add_f32_e32 v136, 1.0, v140
	v_rcp_f32_e32 v140, v136
	v_fmac_f32_e32 v132, v49, v194
	v_fmac_f32_e32 v133, v57, v195
	v_mul_f32_e32 v134, 0xbfb8aa3b, v133
	v_exp_f32_e32 v136, v134
	v_pk_fma_f32 v[128:129], v[206:207], v[128:129], v[130:131]
	v_mul_f32_e32 v131, v139, v140
	v_fmac_f32_e32 v128, v48, v208
	v_fmac_f32_e32 v129, v56, v209
	v_add_f32_e32 v134, 1.0, v136
	v_mul_f32_e32 v130, 0xbfb8aa3b, v129
	v_exp_f32_e32 v130, v130
	v_rcp_f32_e32 v134, v134
	v_mul_f32_e32 v131, v138, v131
	v_add_f32_e32 v130, 1.0, v130
	v_rcp_f32_e32 v130, v130
	v_mul_f32_e32 v133, v133, v134
	v_mul_f32_e32 v132, v132, v133
	v_mul_f32_e32 v129, v129, v130
	v_mul_f32_e32 v128, v128, v129
	v_cvt_pk_bf16_f32 v128, v128, v132
	v_cvt_pk_bf16_f32 v129, v131, v141
	v_mov_b64_e32 v[130:131], s[66:67]
	v_mad_i64_i32 v[130:131], s[14:15], v163, s97, v[130:131]
	v_lshl_add_u64 v[130:131], v[178:179], 1, v[130:131]
	global_store_dwordx2 v[130:131], v[128:129], off offset:8
.LBB0_840:
	s_or_b64 exec, exec, s[38:39]
	v_mov_b32_dpp v143, v59 row_ror:2 row_mask:0xf bank_mask:0xf
	v_mov_b32_dpp v142, v51 row_ror:2 row_mask:0xf bank_mask:0xf
	v_mov_b32_dpp v141, v59 row_ror:1 row_mask:0xf bank_mask:0xf
	v_mov_b32_dpp v143, v43 row_shr:2 row_mask:0xf bank_mask:0xf
	v_mov_b32_dpp v140, v51 row_ror:1 row_mask:0xf bank_mask:0xf
	v_mov_b32_dpp v142, v35 row_shr:2 row_mask:0xf bank_mask:0xf
	v_mov_b32_dpp v141, v43 row_shr:1 row_mask:0xf bank_mask:0xf
	v_mov_b32_dpp v140, v35 row_shr:1 row_mask:0xf bank_mask:0xf
	v_pk_fma_f32 v[142:143], v[214:215], v[142:143], v[216:217]
	v_pk_fma_f32 v[140:141], v[212:213], v[140:141], v[142:143]
	v_fmac_f32_e32 v140, v35, v210
	v_fmac_f32_e32 v141, v43, v211
	v_mul_f32_e32 v138, 0xbfb8aa3b, v141
	v_exp_f32_e32 v142, v138
	v_mov_b32_dpp v139, v58 row_ror:2 row_mask:0xf bank_mask:0xf
	v_mov_b32_dpp v138, v50 row_ror:2 row_mask:0xf bank_mask:0xf
	v_mov_b32_dpp v137, v58 row_ror:1 row_mask:0xf bank_mask:0xf
	v_mov_b32_dpp v139, v42 row_shr:2 row_mask:0xf bank_mask:0xf
	v_mov_b32_dpp v136, v50 row_ror:1 row_mask:0xf bank_mask:0xf
	v_mov_b32_dpp v138, v34 row_shr:2 row_mask:0xf bank_mask:0xf
	v_mov_b32_dpp v137, v42 row_shr:1 row_mask:0xf bank_mask:0xf
	v_mov_b32_dpp v136, v34 row_shr:1 row_mask:0xf bank_mask:0xf
	v_add_f32_e32 v142, 1.0, v142
	v_pk_fma_f32 v[138:139], v[220:221], v[138:139], v[218:219]
	v_rcp_f32_e32 v144, v142
	v_pk_fma_f32 v[136:137], v[222:223], v[136:137], v[138:139]
	v_fmac_f32_e32 v136, v34, v224
	v_fmac_f32_e32 v137, v42, v225
	v_mul_f32_e32 v138, 0xbfb8aa3b, v137
	v_exp_f32_e32 v138, v138
	v_mov_b32_dpp v135, v57 row_ror:2 row_mask:0xf bank_mask:0xf
	v_mov_b32_dpp v134, v49 row_ror:2 row_mask:0xf bank_mask:0xf
	v_mov_b32_dpp v133, v57 row_ror:1 row_mask:0xf bank_mask:0xf
	v_mov_b32_dpp v135, v41 row_shr:2 row_mask:0xf bank_mask:0xf
	v_mov_b32_dpp v132, v49 row_ror:1 row_mask:0xf bank_mask:0xf
	v_mov_b32_dpp v134, v33 row_shr:2 row_mask:0xf bank_mask:0xf
	v_mov_b32_dpp v133, v41 row_shr:1 row_mask:0xf bank_mask:0xf
	v_mov_b32_dpp v132, v33 row_shr:1 row_mask:0xf bank_mask:0xf
	v_mul_f32_e32 v139, v141, v144
	v_add_f32_e32 v138, 1.0, v138
	v_pk_fma_f32 v[134:135], v[198:199], v[134:135], v[200:201]
	v_mov_b32_dpp v131, v56 row_ror:2 row_mask:0xf bank_mask:0xf
	v_mov_b32_dpp v130, v48 row_ror:2 row_mask:0xf bank_mask:0xf
	v_mul_f32_e32 v140, v140, v139
	v_rcp_f32_e32 v141, v138
	v_pk_fma_f32 v[132:133], v[196:197], v[132:133], v[134:135]
	v_mov_b32_dpp v129, v56 row_ror:1 row_mask:0xf bank_mask:0xf
	v_mov_b32_dpp v131, v40 row_shr:2 row_mask:0xf bank_mask:0xf
	v_mov_b32_dpp v128, v48 row_ror:1 row_mask:0xf bank_mask:0xf
	v_mov_b32_dpp v130, v32 row_shr:2 row_mask:0xf bank_mask:0xf
	v_fmac_f32_e32 v132, v33, v194
	v_fmac_f32_e32 v133, v41, v195
	v_mov_b32_dpp v129, v40 row_shr:1 row_mask:0xf bank_mask:0xf
	v_mov_b32_dpp v128, v32 row_shr:1 row_mask:0xf bank_mask:0xf
	v_mul_f32_e32 v134, 0xbfb8aa3b, v133
	v_pk_fma_f32 v[130:131], v[204:205], v[130:131], v[202:203]
	v_exp_f32_e32 v138, v134
	v_pk_fma_f32 v[128:129], v[206:207], v[128:129], v[130:131]
	v_mul_f32_e32 v131, v137, v141
	v_fmac_f32_e32 v128, v32, v208
	v_fmac_f32_e32 v129, v40, v209
	v_add_f32_e32 v134, 1.0, v138
	v_mul_f32_e32 v130, 0xbfb8aa3b, v129
	v_exp_f32_e32 v130, v130
	v_rcp_f32_e32 v134, v134
	v_mul_f32_e32 v131, v136, v131
	v_add_f32_e32 v130, 1.0, v130
	v_rcp_f32_e32 v130, v130
	v_mul_f32_e32 v133, v133, v134
	v_mul_f32_e32 v132, v132, v133
	v_mul_f32_e32 v129, v129, v130
	v_mul_f32_e32 v128, v128, v129
	v_cvt_pk_bf16_f32 v128, v128, v132
	v_cvt_pk_bf16_f32 v129, v131, v140
	global_store_dwordx2 v[188:189], v[128:129], off offset:8
	v_mov_b32_dpp v143, v43 row_ror:2 row_mask:0xf bank_mask:0xf
	v_mov_b32_dpp v142, v35 row_ror:2 row_mask:0xf bank_mask:0xf
	v_mov_b32_dpp v141, v43 row_ror:1 row_mask:0xf bank_mask:0xf
	v_mov_b32_dpp v143, v27 row_shr:2 row_mask:0xf bank_mask:0xf
; DI float frcp(float x) { return __builtin_amdgcn_rcpf(x); }
; DI u32x2 pack4(const f32x4 a) { u32x2 w; w.x = cvt_pk_bf16(a[0], a[1]); w.y = cvt_pk_bf16(a[2], a[3]); return w; }
;     DI void operator()(const pg8::f32x4 (&acc)[2][2][4][2], const pg8::Unit& u, int wr, int wc, int fr, int fq) const {
;     ...
;                 for (int m = 0; m < 4; ++m) {
;                     const f32x4 cg = acc[ai][0][m][q], cv = acc[ai][1][m][q];
;                     const f32x4 pg = m > 0 ? acc[ai][0][m > 0 ? m - 1 : 0][q] : (f32x4){0.f, 0.f, 0.f, 0.f}, pv = m > 0 ? acc[ai][1][m > 0 ? m - 1 : 0][q] : (f32x4){0.f, 0.f, 0.f, 0.f};
;                     f32x4 o;
; #pragma unroll
;                     for (int e = 0; e < 4; ++e) {
;                         const float g1 = row_shift<1>(cg[e], pg[e]), g2 = row_shift<2>(cg[e], pg[e]), v1 = row_shift<1>(cv[e], pv[e]), v2 = row_shift<2>(cv[e], pv[e]);
;                         const float a = bg[e] + kg0[e] * g2 + kg1[e] * g1 + kg2[e] * cg[e], b = bv[e] + kv0[e] * v2 + kv1[e] * v1 + kv2[e] * cv[e];
;                         o[e] = a * frcp(1.f + __expf(-a)) * b;
;                     }
;                     const int r = u.pm * 256 + ai * 128 + wr * 64 + m * 16 + fr;
;                     if (m > 0 || fr >= 2) *(u32x2*)(ACT + (size_t)r * DFF + j0 + 4 * q) = pack4(o);
;                     __builtin_amdgcn_sched_barrier(0);
;                 }
	v_mov_b32_dpp v140, v35 row_ror:1 row_mask:0xf bank_mask:0xf
	v_mov_b32_dpp v142, v19 row_shr:2 row_mask:0xf bank_mask:0xf
	v_mov_b32_dpp v141, v27 row_shr:1 row_mask:0xf bank_mask:0xf
	v_mov_b32_dpp v140, v19 row_shr:1 row_mask:0xf bank_mask:0xf
	v_pk_fma_f32 v[142:143], v[214:215], v[142:143], v[216:217]
	v_pk_fma_f32 v[140:141], v[212:213], v[140:141], v[142:143]
	v_fmac_f32_e32 v140, v19, v210
	v_fmac_f32_e32 v141, v27, v211
	v_mul_f32_e32 v138, 0xbfb8aa3b, v141
	v_exp_f32_e32 v142, v138
	v_mov_b32_dpp v139, v42 row_ror:2 row_mask:0xf bank_mask:0xf
	v_mov_b32_dpp v138, v34 row_ror:2 row_mask:0xf bank_mask:0xf
	v_mov_b32_dpp v137, v42 row_ror:1 row_mask:0xf bank_mask:0xf
	v_mov_b32_dpp v139, v26 row_shr:2 row_mask:0xf bank_mask:0xf
	v_mov_b32_dpp v136, v34 row_ror:1 row_mask:0xf bank_mask:0xf
	v_mov_b32_dpp v138, v18 row_shr:2 row_mask:0xf bank_mask:0xf
	v_mov_b32_dpp v137, v26 row_shr:1 row_mask:0xf bank_mask:0xf
	v_mov_b32_dpp v136, v18 row_shr:1 row_mask:0xf bank_mask:0xf
	v_add_f32_e32 v142, 1.0, v142
	v_pk_fma_f32 v[138:139], v[220:221], v[138:139], v[218:219]
	v_rcp_f32_e32 v144, v142
	v_pk_fma_f32 v[136:137], v[222:223], v[136:137], v[138:139]
	v_fmac_f32_e32 v136, v18, v224
	v_fmac_f32_e32 v137, v26, v225
	v_mul_f32_e32 v138, 0xbfb8aa3b, v137
	v_exp_f32_e32 v138, v138
	v_mov_b32_dpp v135, v41 row_ror:2 row_mask:0xf bank_mask:0xf
	v_mov_b32_dpp v134, v33 row_ror:2 row_mask:0xf bank_mask:0xf
	v_mov_b32_dpp v133, v41 row_ror:1 row_mask:0xf bank_mask:0xf
	v_mov_b32_dpp v135, v25 row_shr:2 row_mask:0xf bank_mask:0xf
	v_mov_b32_dpp v132, v33 row_ror:1 row_mask:0xf bank_mask:0xf
	v_mov_b32_dpp v134, v17 row_shr:2 row_mask:0xf bank_mask:0xf
	v_mov_b32_dpp v133, v25 row_shr:1 row_mask:0xf bank_mask:0xf
	v_mov_b32_dpp v132, v17 row_shr:1 row_mask:0xf bank_mask:0xf
	v_mul_f32_e32 v139, v141, v144
	v_add_f32_e32 v138, 1.0, v138
	v_pk_fma_f32 v[134:135], v[198:199], v[134:135], v[200:201]
	v_mov_b32_dpp v131, v40 row_ror:2 row_mask:0xf bank_mask:0xf
	v_mov_b32_dpp v130, v32 row_ror:2 row_mask:0xf bank_mask:0xf
	v_mul_f32_e32 v140, v140, v139
	v_rcp_f32_e32 v141, v138
	v_pk_fma_f32 v[132:133], v[196:197], v[132:133], v[134:135]
	v_mov_b32_dpp v129, v40 row_ror:1 row_mask:0xf bank_mask:0xf
	v_mov_b32_dpp v131, v24 row_shr:2 row_mask:0xf bank_mask:0xf
	v_mov_b32_dpp v128, v32 row_ror:1 row_mask:0xf bank_mask:0xf
	v_mov_b32_dpp v130, v16 row_shr:2 row_mask:0xf bank_mask:0xf
	v_fmac_f32_e32 v132, v17, v194
	v_fmac_f32_e32 v133, v25, v195
	v_mov_b32_dpp v129, v24 row_shr:1 row_mask:0xf bank_mask:0xf
	v_mov_b32_dpp v128, v16 row_shr:1 row_mask:0xf bank_mask:0xf
	v_mul_f32_e32 v134, 0xbfb8aa3b, v133
	v_pk_fma_f32 v[130:131], v[204:205], v[130:131], v[202:203]
	v_exp_f32_e32 v138, v134
	v_pk_fma_f32 v[128:129], v[206:207], v[128:129], v[130:131]
	v_mul_f32_e32 v131, v137, v141
	v_fmac_f32_e32 v128, v16, v208
	v_fmac_f32_e32 v129, v24, v209
	v_add_f32_e32 v134, 1.0, v138
	v_mul_f32_e32 v130, 0xbfb8aa3b, v129
	v_exp_f32_e32 v130, v130
	v_rcp_f32_e32 v134, v134
	v_mul_f32_e32 v131, v136, v131
	v_add_f32_e32 v130, 1.0, v130
	v_rcp_f32_e32 v130, v130
	v_mul_f32_e32 v133, v133, v134
	v_mul_f32_e32 v132, v132, v133
	v_mul_f32_e32 v129, v129, v130
	v_mul_f32_e32 v128, v128, v129
	v_cvt_pk_bf16_f32 v128, v128, v132
	v_cvt_pk_bf16_f32 v129, v131, v140
	global_store_dwordx2 v[190:191], v[128:129], off offset:8
	v_mov_b32_dpp v143, v27 row_ror:2 row_mask:0xf bank_mask:0xf
	v_mov_b32_dpp v142, v19 row_ror:2 row_mask:0xf bank_mask:0xf
	v_mov_b32_dpp v141, v27 row_ror:1 row_mask:0xf bank_mask:0xf
	v_mov_b32_dpp v143, v11 row_shr:2 row_mask:0xf bank_mask:0xf
	v_mov_b32_dpp v140, v19 row_ror:1 row_mask:0xf bank_mask:0xf
	v_mov_b32_dpp v142, v3 row_shr:2 row_mask:0xf bank_mask:0xf
	v_mov_b32_dpp v141, v11 row_shr:1 row_mask:0xf bank_mask:0xf
	v_mov_b32_dpp v140, v3 row_shr:1 row_mask:0xf bank_mask:0xf
	v_pk_fma_f32 v[142:143], v[214:215], v[142:143], v[216:217]
	v_pk_fma_f32 v[140:141], v[212:213], v[140:141], v[142:143]
	v_fmac_f32_e32 v140, v3, v210
	v_fmac_f32_e32 v141, v11, v211
	v_mul_f32_e32 v138, 0xbfb8aa3b, v141
	v_exp_f32_e32 v142, v138
	v_mov_b32_dpp v139, v26 row_ror:2 row_mask:0xf bank_mask:0xf
	v_mov_b32_dpp v138, v18 row_ror:2 row_mask:0xf bank_mask:0xf
	v_mov_b32_dpp v137, v26 row_ror:1 row_mask:0xf bank_mask:0xf
	v_mov_b32_dpp v139, v10 row_shr:2 row_mask:0xf bank_mask:0xf
	v_mov_b32_dpp v136, v18 row_ror:1 row_mask:0xf bank_mask:0xf
	v_mov_b32_dpp v138, v2 row_shr:2 row_mask:0xf bank_mask:0xf
	v_mov_b32_dpp v137, v10 row_shr:1 row_mask:0xf bank_mask:0xf
	v_mov_b32_dpp v136, v2 row_shr:1 row_mask:0xf bank_mask:0xf
	v_add_f32_e32 v142, 1.0, v142
	v_pk_fma_f32 v[138:139], v[220:221], v[138:139], v[218:219]
	v_rcp_f32_e32 v144, v142
	v_pk_fma_f32 v[136:137], v[222:223], v[136:137], v[138:139]
	v_fmac_f32_e32 v136, v2, v224
	v_fmac_f32_e32 v137, v10, v225
	v_mul_f32_e32 v138, 0xbfb8aa3b, v137
	v_exp_f32_e32 v138, v138
	v_mov_b32_dpp v135, v25 row_ror:2 row_mask:0xf bank_mask:0xf
	v_mov_b32_dpp v134, v17 row_ror:2 row_mask:0xf bank_mask:0xf
	v_mov_b32_dpp v133, v25 row_ror:1 row_mask:0xf bank_mask:0xf
	v_mov_b32_dpp v135, v9 row_shr:2 row_mask:0xf bank_mask:0xf
	v_mov_b32_dpp v132, v17 row_ror:1 row_mask:0xf bank_mask:0xf
	v_mov_b32_dpp v134, v1 row_shr:2 row_mask:0xf bank_mask:0xf
	v_mov_b32_dpp v133, v9 row_shr:1 row_mask:0xf bank_mask:0xf
	v_mov_b32_dpp v132, v1 row_shr:1 row_mask:0xf bank_mask:0xf
	v_mul_f32_e32 v139, v141, v144
	v_add_f32_e32 v138, 1.0, v138
	v_pk_fma_f32 v[134:135], v[198:199], v[134:135], v[200:201]
	v_mov_b32_dpp v131, v24 row_ror:2 row_mask:0xf bank_mask:0xf
	v_mov_b32_dpp v130, v16 row_ror:2 row_mask:0xf bank_mask:0xf
	v_mul_f32_e32 v140, v140, v139
	v_rcp_f32_e32 v141, v138
	v_pk_fma_f32 v[132:133], v[196:197], v[132:133], v[134:135]
	v_mov_b32_dpp v129, v24 row_ror:1 row_mask:0xf bank_mask:0xf
	v_mov_b32_dpp v131, v8 row_shr:2 row_mask:0xf bank_mask:0xf
	v_mov_b32_dpp v128, v16 row_ror:1 row_mask:0xf bank_mask:0xf
	v_mov_b32_dpp v130, v0 row_shr:2 row_mask:0xf bank_mask:0xf
	v_fmac_f32_e32 v132, v1, v194
	v_fmac_f32_e32 v133, v9, v195
	v_mov_b32_dpp v129, v8 row_shr:1 row_mask:0xf bank_mask:0xf
	v_mov_b32_dpp v128, v0 row_shr:1 row_mask:0xf bank_mask:0xf
	v_mul_f32_e32 v134, 0xbfb8aa3b, v133
	v_pk_fma_f32 v[130:131], v[204:205], v[130:131], v[202:203]
	v_exp_f32_e32 v138, v134
	v_pk_fma_f32 v[128:129], v[206:207], v[128:129], v[130:131]
	v_mul_f32_e32 v131, v137, v141
	v_fmac_f32_e32 v128, v0, v208
	v_fmac_f32_e32 v129, v8, v209
	v_add_f32_e32 v134, 1.0, v138
	v_mul_f32_e32 v130, 0xbfb8aa3b, v129
	v_exp_f32_e32 v130, v130
	v_rcp_f32_e32 v134, v134
	v_mul_f32_e32 v131, v136, v131
	v_add_f32_e32 v130, 1.0, v130
	v_rcp_f32_e32 v130, v130
	v_mul_f32_e32 v133, v133, v134
	v_mul_f32_e32 v132, v132, v133
	v_mul_f32_e32 v129, v129, v130
	v_mul_f32_e32 v128, v128, v129
	v_cvt_pk_bf16_f32 v128, v128, v132
	v_cvt_pk_bf16_f32 v129, v131, v140
	global_store_dwordx2 v[192:193], v[128:129], off offset:8
